# GEMM mainloops: all per-segment s_setprio toggles removed (static priority), rest as the combination version
# speedup vs baseline: 1.0085x; 1.0036x over previous
; #define PG8_STAGE(bufoff, gbase, voff) do { _Pragma("unroll") for (int _i = 0; _i < 2; ++_i) \
;         __builtin_amdgcn_global_load_lds((const unsigned*)((const char*)(gbase) + (voff)[_i]), (LAS unsigned*)(lds + (bufoff) + ldsw + _i * 8192), 16, 0, 0); } while (0)
; #define PG8_LDA(dst, b, h) do { _Pragma("unroll") for (int m = 0; m < 4; ++m) _Pragma("unroll") for (int k = 0; k < 2; ++k) dst[m][k] = *(const LAS bf16x8*)(lds + PG8_SA(b, h) + aoff + m * 2048 + k * 1024); } while (0)
; #define PG8_LDB(dst, b, h) do { _Pragma("unroll") for (int n = 0; n < 2; ++n) _Pragma("unroll") for (int k = 0; k < 2; ++k) dst[n][k] = *(const LAS bf16x8*)(lds + PG8_SB(b, h) + boff + n * 2048 + k * 1024); } while (0)
; #define PG8_MMA(ai, bj, At, Bt) do { __builtin_amdgcn_s_setprio(1); _Pragma("unroll") for (int m = 0; m < 4; ++m) _Pragma("unroll") for (int n = 0; n < 2; ++n) _Pragma("unroll") for (int k = 0; k < 2; ++k) \
;         acc[ai][bj][m][n] = __builtin_amdgcn_mfma_f32_16x16x32_bf16(Bt[n][k], At[m][k], acc[ai][bj][m][n], 0, 0, 0); __builtin_amdgcn_s_setprio(0); } while (0)
; #define PG8_WAIT_V(n) asm volatile("s_waitcnt vmcnt(" #n ")" ::: "memory")
; #define PG8_WAIT_L(n) asm volatile("s_waitcnt lgkmcnt(" #n ")" ::: "memory")
; #define PG8_BAR __builtin_amdgcn_s_barrier()
; template <class Epi, class Sched>
; __device__ __forceinline__ void gemm_phase(LAS unsigned char* lds, const Gemm g, const Sched& S, const Epi& E, const int wv) {
;     ...
;         for (int t = 0; t < nt; t += 2) {
;             const bool last = (t == nt - 2);
;             const char* a1 = cA + (size_t)(t + 1) * kstep;
;             const char* a2 = last ? nA : cA + (size_t)(t + 2) * kstep; const char* b2 = last ? nB : cB + (size_t)(t + 2) * kstep;
;             const char* a3 = a2 + kstep; const char* b3 = b2 + kstep;
;             if (last && has_next) S.a_ready(nxt);
;             PG8_LDB(B0, 0, 0); PG8_LDB(B1, 0, 1); PG8_SCHED; PG8_LDA(At, 0, 0); PG8_STAGE(PG8_SA(1, 1), a1 + hstep, voffA);
;             PG8_WAIT_V(8); PG8_WAIT_L(0); PG8_BAR; PG8_MMA(0, 0, At, B0); PG8_MMA(0, 1, At, B1); PG8_BAR; PG8_SCHED;
;             PG8_LDA(At, 0, 1); PG8_STAGE(PG8_SB(0, 0), b2, voffB); PG8_STAGE(PG8_SB(0, 1), b2 + hstep, voffB); PG8_STAGE(PG8_SA(0, 0), a2, voffA);
;             PG8_WAIT_V(8); PG8_WAIT_L(0); PG8_BAR; PG8_MMA(1, 0, At, B0); PG8_MMA(1, 1, At, B1); PG8_BAR; PG8_SCHED;
.LBB0_27:
	s_add_u32 s10, s16, 0xfff80080
	s_addc_u32 s11, s17, -1
	s_add_i32 s65, 0, 0x10000
	s_cmp_eq_u32 s52, 28
	s_cselect_b32 s13, s23, s11
	s_cselect_b32 s12, s42, s10
	v_add_u32_e32 v138, s65, v141
	s_cselect_b32 s11, s21, s45
	s_cselect_b32 s10, s43, s44
	s_add_i32 s77, 0, 0x14000
	ds_read_b128 v[144:147], v138
	ds_read_b128 v[148:151], v138 offset:1024
	ds_read_b128 v[152:155], v138 offset:2048
	ds_read_b128 v[156:159], v138 offset:3072
	v_add_u32_e32 v138, s77, v141
	ds_read_b128 v[160:163], v138
	ds_read_b128 v[164:167], v138 offset:1024
	ds_read_b128 v[168:171], v138 offset:2048
	ds_read_b128 v[172:175], v138 offset:3072
	v_lshl_add_u64 v[138:139], s[16:17], 0, v[134:135]
	s_add_i32 m0, s31, 0xc000
	ds_read_b128 v[176:179], v143
	ds_read_b128 v[180:183], v143 offset:1024
	ds_read_b128 v[184:187], v143 offset:2048
	ds_read_b128 v[188:191], v143 offset:3072
	ds_read_b128 v[192:195], v143 offset:4096
	ds_read_b128 v[196:199], v143 offset:5120
	ds_read_b128 v[200:203], v143 offset:6144
	ds_read_b128 v[204:207], v143 offset:7168
	global_load_lds_dwordx4 v[138:139], off
	v_lshl_add_u64 v[138:139], s[16:17], 0, v[136:137]
	s_add_i32 m0, s31, 0xe000
	s_nop 0
	global_load_lds_dwordx4 v[138:139], off
	s_waitcnt vmcnt(8)
	s_waitcnt lgkmcnt(0)
	s_barrier
	s_waitcnt lgkmcnt(0)
	v_mfma_f32_16x16x32_bf16 v[124:127], v[144:147], v[176:179], v[124:127]
	v_mfma_f32_16x16x32_bf16 v[116:119], v[152:155], v[176:179], v[116:119]
	v_mfma_f32_16x16x32_bf16 v[108:111], v[144:147], v[184:187], v[108:111]
	v_mfma_f32_16x16x32_bf16 v[100:103], v[152:155], v[184:187], v[100:103]
	v_mfma_f32_16x16x32_bf16 v[92:95], v[144:147], v[192:195], v[92:95]
	v_mfma_f32_16x16x32_bf16 v[84:87], v[152:155], v[192:195], v[84:87]
	v_mfma_f32_16x16x32_bf16 v[76:79], v[144:147], v[200:203], v[76:79]
	v_mfma_f32_16x16x32_bf16 v[68:71], v[152:155], v[200:203], v[68:71]
	v_mfma_f32_16x16x32_bf16 v[124:127], v[148:151], v[180:183], v[124:127]
	v_mfma_f32_16x16x32_bf16 v[116:119], v[156:159], v[180:183], v[116:119]
	v_mfma_f32_16x16x32_bf16 v[108:111], v[148:151], v[188:191], v[108:111]
	v_mfma_f32_16x16x32_bf16 v[100:103], v[156:159], v[188:191], v[100:103]
	v_mfma_f32_16x16x32_bf16 v[92:95], v[148:151], v[196:199], v[92:95]
	v_mfma_f32_16x16x32_bf16 v[84:87], v[156:159], v[196:199], v[84:87]
	v_mfma_f32_16x16x32_bf16 v[76:79], v[148:151], v[204:207], v[76:79]
	v_mfma_f32_16x16x32_bf16 v[68:71], v[156:159], v[204:207], v[68:71]
	v_mfma_f32_16x16x32_bf16 v[120:123], v[160:163], v[176:179], v[120:123]
	v_mfma_f32_16x16x32_bf16 v[112:115], v[168:171], v[176:179], v[112:115]
	v_mfma_f32_16x16x32_bf16 v[104:107], v[160:163], v[184:187], v[104:107]
	v_mfma_f32_16x16x32_bf16 v[96:99], v[168:171], v[184:187], v[96:99]
	v_mfma_f32_16x16x32_bf16 v[88:91], v[160:163], v[192:195], v[88:91]
	v_mfma_f32_16x16x32_bf16 v[80:83], v[168:171], v[192:195], v[80:83]
	v_mfma_f32_16x16x32_bf16 v[72:75], v[160:163], v[200:203], v[72:75]
	v_mfma_f32_16x16x32_bf16 v[64:67], v[168:171], v[200:203], v[64:67]
	v_mfma_f32_16x16x32_bf16 v[120:123], v[164:167], v[180:183], v[120:123]
	v_mfma_f32_16x16x32_bf16 v[112:115], v[172:175], v[180:183], v[112:115]
	v_mfma_f32_16x16x32_bf16 v[104:107], v[164:167], v[188:191], v[104:107]
	v_mfma_f32_16x16x32_bf16 v[96:99], v[172:175], v[188:191], v[96:99]
	v_mfma_f32_16x16x32_bf16 v[88:91], v[164:167], v[196:199], v[88:91]
	v_mfma_f32_16x16x32_bf16 v[80:83], v[172:175], v[196:199], v[80:83]
	v_mfma_f32_16x16x32_bf16 v[72:75], v[164:167], v[204:207], v[72:75]
	v_mfma_f32_16x16x32_bf16 v[64:67], v[172:175], v[204:207], v[64:67]
	s_barrier
	s_add_i32 s65, s65, s30
	v_lshl_add_u64 v[138:139], s[10:11], 0, v[210:211]
	s_mov_b32 m0, s65
	ds_read_b128 v[176:179], v143 offset:16384
	ds_read_b128 v[180:183], v143 offset:17408
	ds_read_b128 v[184:187], v143 offset:18432
	ds_read_b128 v[188:191], v143 offset:19456
	ds_read_b128 v[192:195], v143 offset:20480
	ds_read_b128 v[196:199], v143 offset:21504
	ds_read_b128 v[200:203], v143 offset:22528
	ds_read_b128 v[204:207], v143 offset:23552
	global_load_lds_dwordx4 v[138:139], off
	s_add_i32 m0, s65, 0x2000
	s_add_u32 s82, s10, 0x80000
	v_lshl_add_u64 v[208:209], s[10:11], 0, v[128:129]
	s_addc_u32 s83, s11, 0
	s_add_i32 s65, s77, s30
	global_load_lds_dwordx4 v[208:209], off
	v_lshl_add_u64 v[212:213], s[82:83], 0, v[210:211]
	s_mov_b32 m0, s65
	v_lshl_add_u64 v[214:215], s[12:13], 0, v[130:131]
	global_load_lds_dwordx4 v[212:213], off
	v_lshl_add_u64 v[212:213], s[82:83], 0, v[128:129]
	s_add_i32 m0, s65, 0x2000
	s_nop 0
	global_load_lds_dwordx4 v[212:213], off
	v_lshl_add_u64 v[212:213], s[12:13], 0, v[132:133]
	s_mov_b32 m0, s31
	s_nop 0
	global_load_lds_dwordx4 v[212:213], off
	s_mov_b32 m0, s34
	s_nop 0
	global_load_lds_dwordx4 v[214:215], off
	s_waitcnt vmcnt(8)
	s_waitcnt lgkmcnt(0)
	s_barrier
; #define PG8_STAGE(bufoff, gbase, voff) do { _Pragma("unroll") for (int _i = 0; _i < 2; ++_i) \
;         __builtin_amdgcn_global_load_lds((const unsigned*)((const char*)(gbase) + (voff)[_i]), (LAS unsigned*)(lds + (bufoff) + ldsw + _i * 8192), 16, 0, 0); } while (0)
; #define PG8_LDA(dst, b, h) do { _Pragma("unroll") for (int m = 0; m < 4; ++m) _Pragma("unroll") for (int k = 0; k < 2; ++k) dst[m][k] = *(const LAS bf16x8*)(lds + PG8_SA(b, h) + aoff + m * 2048 + k * 1024); } while (0)
; #define PG8_LDB(dst, b, h) do { _Pragma("unroll") for (int n = 0; n < 2; ++n) _Pragma("unroll") for (int k = 0; k < 2; ++k) dst[n][k] = *(const LAS bf16x8*)(lds + PG8_SB(b, h) + boff + n * 2048 + k * 1024); } while (0)
; #define PG8_MMA(ai, bj, At, Bt) do { __builtin_amdgcn_s_setprio(1); _Pragma("unroll") for (int m = 0; m < 4; ++m) _Pragma("unroll") for (int n = 0; n < 2; ++n) _Pragma("unroll") for (int k = 0; k < 2; ++k) \
;         acc[ai][bj][m][n] = __builtin_amdgcn_mfma_f32_16x16x32_bf16(Bt[n][k], At[m][k], acc[ai][bj][m][n], 0, 0, 0); __builtin_amdgcn_s_setprio(0); } while (0)
; #define PG8_WAIT_V(n) asm volatile("s_waitcnt vmcnt(" #n ")" ::: "memory")
; #define PG8_WAIT_L(n) asm volatile("s_waitcnt lgkmcnt(" #n ")" ::: "memory")
; #define PG8_BAR __builtin_amdgcn_s_barrier()
; #define PG8_SCHED __builtin_amdgcn_sched_barrier(0)
; template <class Epi, class Sched>
; __device__ __forceinline__ void gemm_phase(LAS unsigned char* lds, const Gemm g, const Sched& S, const Epi& E, const int wv) {
;     ...
;             PG8_WAIT_V(8); PG8_WAIT_L(0); PG8_BAR; PG8_MMA(1, 0, At, B0); PG8_MMA(1, 1, At, B1); PG8_BAR; PG8_SCHED;
;             PG8_LDB(B0, 1, 0); PG8_LDB(B1, 1, 1); PG8_SCHED; PG8_LDA(At, 1, 0); PG8_STAGE(PG8_SA(0, 1), a2 + hstep, voffA);
;             PG8_WAIT_V(8); PG8_WAIT_L(0); PG8_BAR; PG8_MMA(0, 0, At, B0); PG8_MMA(0, 1, At, B1); PG8_BAR; PG8_SCHED;
	s_waitcnt lgkmcnt(0)
	v_mfma_f32_16x16x32_bf16 v[60:63], v[144:147], v[176:179], v[60:63]
	v_mfma_f32_16x16x32_bf16 v[52:55], v[152:155], v[176:179], v[52:55]
	v_mfma_f32_16x16x32_bf16 v[44:47], v[144:147], v[184:187], v[44:47]
	v_mfma_f32_16x16x32_bf16 v[36:39], v[152:155], v[184:187], v[36:39]
	v_mfma_f32_16x16x32_bf16 v[28:31], v[144:147], v[192:195], v[28:31]
	v_mfma_f32_16x16x32_bf16 v[20:23], v[152:155], v[192:195], v[20:23]
	v_mfma_f32_16x16x32_bf16 v[12:15], v[144:147], v[200:203], v[12:15]
	v_mfma_f32_16x16x32_bf16 v[4:7], v[152:155], v[200:203], v[4:7]
	v_mfma_f32_16x16x32_bf16 v[60:63], v[148:151], v[180:183], v[60:63]
	v_mfma_f32_16x16x32_bf16 v[52:55], v[156:159], v[180:183], v[52:55]
	v_mfma_f32_16x16x32_bf16 v[44:47], v[148:151], v[188:191], v[44:47]
	v_mfma_f32_16x16x32_bf16 v[36:39], v[156:159], v[188:191], v[36:39]
	v_mfma_f32_16x16x32_bf16 v[28:31], v[148:151], v[196:199], v[28:31]
	v_mfma_f32_16x16x32_bf16 v[20:23], v[156:159], v[196:199], v[20:23]
	v_mfma_f32_16x16x32_bf16 v[12:15], v[148:151], v[204:207], v[12:15]
	v_mfma_f32_16x16x32_bf16 v[4:7], v[156:159], v[204:207], v[4:7]
	v_mfma_f32_16x16x32_bf16 v[56:59], v[160:163], v[176:179], v[56:59]
	v_mfma_f32_16x16x32_bf16 v[48:51], v[168:171], v[176:179], v[48:51]
	v_mfma_f32_16x16x32_bf16 v[40:43], v[160:163], v[184:187], v[40:43]
	v_mfma_f32_16x16x32_bf16 v[32:35], v[168:171], v[184:187], v[32:35]
	v_mfma_f32_16x16x32_bf16 v[24:27], v[160:163], v[192:195], v[24:27]
	v_mfma_f32_16x16x32_bf16 v[16:19], v[168:171], v[192:195], v[16:19]
	v_mfma_f32_16x16x32_bf16 v[8:11], v[160:163], v[200:203], v[8:11]
	v_mfma_f32_16x16x32_bf16 v[0:3], v[168:171], v[200:203], v[0:3]
	v_mfma_f32_16x16x32_bf16 v[56:59], v[164:167], v[180:183], v[56:59]
	v_mfma_f32_16x16x32_bf16 v[48:51], v[172:175], v[180:183], v[48:51]
	v_mfma_f32_16x16x32_bf16 v[40:43], v[164:167], v[188:191], v[40:43]
	v_mfma_f32_16x16x32_bf16 v[32:35], v[172:175], v[188:191], v[32:35]
	v_mfma_f32_16x16x32_bf16 v[24:27], v[164:167], v[196:199], v[24:27]
	v_mfma_f32_16x16x32_bf16 v[16:19], v[172:175], v[196:199], v[16:19]
	v_mfma_f32_16x16x32_bf16 v[8:11], v[164:167], v[204:207], v[8:11]
	v_mfma_f32_16x16x32_bf16 v[0:3], v[172:175], v[204:207], v[0:3]
	s_barrier
	s_add_i32 s65, 0, 0x18000
	s_add_i32 s77, 0, 0x1c000
	v_add_u32_e32 v156, s65, v141
	v_add_u32_e32 v172, s77, v141
	ds_read_b128 v[144:147], v156
	ds_read_b128 v[148:151], v156 offset:1024
	ds_read_b128 v[152:155], v156 offset:2048
	ds_read_b128 v[156:159], v156 offset:3072
	ds_read_b128 v[160:163], v172
	ds_read_b128 v[164:167], v172 offset:1024
	ds_read_b128 v[168:171], v172 offset:2048
	ds_read_b128 v[172:175], v172 offset:3072
	s_add_u32 s12, s12, 0x80000
	s_addc_u32 s13, s13, 0
	s_mov_b32 m0, s35
	v_lshl_add_u64 v[216:217], s[12:13], 0, v[132:133]
	ds_read_b128 v[176:179], v143 offset:32768
	ds_read_b128 v[180:183], v143 offset:33792
	ds_read_b128 v[184:187], v143 offset:34816
	ds_read_b128 v[188:191], v143 offset:35840
	ds_read_b128 v[192:195], v143 offset:36864
	ds_read_b128 v[196:199], v143 offset:37888
	ds_read_b128 v[200:203], v143 offset:38912
	ds_read_b128 v[204:207], v143 offset:39936
	global_load_lds_dwordx4 v[216:217], off
	v_lshl_add_u64 v[216:217], s[12:13], 0, v[130:131]
	s_mov_b32 m0, s36
	s_nop 0
	global_load_lds_dwordx4 v[216:217], off
	s_waitcnt vmcnt(8)
	s_waitcnt lgkmcnt(0)
	s_barrier
	s_waitcnt lgkmcnt(0)
	v_mfma_f32_16x16x32_bf16 v[124:127], v[144:147], v[176:179], v[124:127]
	v_mfma_f32_16x16x32_bf16 v[116:119], v[152:155], v[176:179], v[116:119]
	v_mfma_f32_16x16x32_bf16 v[108:111], v[144:147], v[184:187], v[108:111]
	v_mfma_f32_16x16x32_bf16 v[100:103], v[152:155], v[184:187], v[100:103]
	v_mfma_f32_16x16x32_bf16 v[92:95], v[144:147], v[192:195], v[92:95]
	v_mfma_f32_16x16x32_bf16 v[84:87], v[152:155], v[192:195], v[84:87]
	v_mfma_f32_16x16x32_bf16 v[76:79], v[144:147], v[200:203], v[76:79]
	v_mfma_f32_16x16x32_bf16 v[68:71], v[152:155], v[200:203], v[68:71]
	v_mfma_f32_16x16x32_bf16 v[124:127], v[148:151], v[180:183], v[124:127]
	v_mfma_f32_16x16x32_bf16 v[116:119], v[156:159], v[180:183], v[116:119]
	v_mfma_f32_16x16x32_bf16 v[108:111], v[148:151], v[188:191], v[108:111]
	v_mfma_f32_16x16x32_bf16 v[100:103], v[156:159], v[188:191], v[100:103]
	v_mfma_f32_16x16x32_bf16 v[92:95], v[148:151], v[196:199], v[92:95]
	v_mfma_f32_16x16x32_bf16 v[84:87], v[156:159], v[196:199], v[84:87]
	v_mfma_f32_16x16x32_bf16 v[76:79], v[148:151], v[204:207], v[76:79]
	v_mfma_f32_16x16x32_bf16 v[68:71], v[156:159], v[204:207], v[68:71]
	v_mfma_f32_16x16x32_bf16 v[120:123], v[160:163], v[176:179], v[120:123]
	v_mfma_f32_16x16x32_bf16 v[112:115], v[168:171], v[176:179], v[112:115]
	v_mfma_f32_16x16x32_bf16 v[104:107], v[160:163], v[184:187], v[104:107]
	v_mfma_f32_16x16x32_bf16 v[96:99], v[168:171], v[184:187], v[96:99]
	v_mfma_f32_16x16x32_bf16 v[88:91], v[160:163], v[192:195], v[88:91]
	v_mfma_f32_16x16x32_bf16 v[80:83], v[168:171], v[192:195], v[80:83]
	v_mfma_f32_16x16x32_bf16 v[72:75], v[160:163], v[200:203], v[72:75]
	v_mfma_f32_16x16x32_bf16 v[64:67], v[168:171], v[200:203], v[64:67]
	v_mfma_f32_16x16x32_bf16 v[120:123], v[164:167], v[180:183], v[120:123]
	v_mfma_f32_16x16x32_bf16 v[112:115], v[172:175], v[180:183], v[112:115]
	v_mfma_f32_16x16x32_bf16 v[104:107], v[164:167], v[188:191], v[104:107]
	v_mfma_f32_16x16x32_bf16 v[96:99], v[172:175], v[188:191], v[96:99]
	v_mfma_f32_16x16x32_bf16 v[88:91], v[164:167], v[196:199], v[88:91]
	v_mfma_f32_16x16x32_bf16 v[80:83], v[172:175], v[196:199], v[80:83]
	v_mfma_f32_16x16x32_bf16 v[72:75], v[164:167], v[204:207], v[72:75]
	v_mfma_f32_16x16x32_bf16 v[64:67], v[172:175], v[204:207], v[64:67]
	s_barrier
; #define PG8_STAGE(bufoff, gbase, voff) do { _Pragma("unroll") for (int _i = 0; _i < 2; ++_i) \
;         __builtin_amdgcn_global_load_lds((const unsigned*)((const char*)(gbase) + (voff)[_i]), (LAS unsigned*)(lds + (bufoff) + ldsw + _i * 8192), 16, 0, 0); } while (0)
; #define PG8_LDA(dst, b, h) do { _Pragma("unroll") for (int m = 0; m < 4; ++m) _Pragma("unroll") for (int k = 0; k < 2; ++k) dst[m][k] = *(const LAS bf16x8*)(lds + PG8_SA(b, h) + aoff + m * 2048 + k * 1024); } while (0)
; #define PG8_MMA(ai, bj, At, Bt) do { __builtin_amdgcn_s_setprio(1); _Pragma("unroll") for (int m = 0; m < 4; ++m) _Pragma("unroll") for (int n = 0; n < 2; ++n) _Pragma("unroll") for (int k = 0; k < 2; ++k) \
;         acc[ai][bj][m][n] = __builtin_amdgcn_mfma_f32_16x16x32_bf16(Bt[n][k], At[m][k], acc[ai][bj][m][n], 0, 0, 0); __builtin_amdgcn_s_setprio(0); } while (0)
; #define PG8_WAIT_V(n) asm volatile("s_waitcnt vmcnt(" #n ")" ::: "memory")
; #define PG8_WAIT_L(n) asm volatile("s_waitcnt lgkmcnt(" #n ")" ::: "memory")
; #define PG8_BAR __builtin_amdgcn_s_barrier()
; #define PG8_SCHED __builtin_amdgcn_sched_barrier(0)
; template <class Epi, class Sched>
; __device__ __forceinline__ void gemm_phase(LAS unsigned char* lds, const Gemm g, const Sched& S, const Epi& E, const int wv) {
;     ...
;             PG8_LDA(At, 1, 1); PG8_STAGE(PG8_SB(1, 0), b3, voffB); PG8_STAGE(PG8_SB(1, 1), b3 + hstep, voffB); PG8_STAGE(PG8_SA(1, 0), a3, voffA);
;             PG8_WAIT_V(8); PG8_WAIT_L(0); PG8_BAR; PG8_MMA(1, 0, At, B0); PG8_MMA(1, 1, At, B1); PG8_BAR; PG8_SCHED;
;         }
;         if (wr == 0) PG8_BAR;
	s_add_i32 s12, s65, s30
	v_lshl_add_u64 v[138:139], v[138:139], 0, s[46:47]
	s_mov_b32 m0, s12
	ds_read_b128 v[176:179], v143 offset:49152
	ds_read_b128 v[180:183], v143 offset:50176
	ds_read_b128 v[184:187], v143 offset:51200
	ds_read_b128 v[188:191], v143 offset:52224
	ds_read_b128 v[192:195], v143 offset:53248
	ds_read_b128 v[196:199], v143 offset:54272
	ds_read_b128 v[200:203], v143 offset:55296
	ds_read_b128 v[204:207], v143 offset:56320
	global_load_lds_dwordx4 v[138:139], off
	s_add_i32 m0, s12, 0x2000
	s_add_u32 s10, s10, 0x80080
	v_lshl_add_u64 v[138:139], v[208:209], 0, s[46:47]
	s_addc_u32 s11, s11, 0
	s_add_i32 s12, s77, s30
	global_load_lds_dwordx4 v[138:139], off
	v_lshl_add_u64 v[138:139], s[10:11], 0, v[210:211]
	s_mov_b32 m0, s12
	s_nop 0
	global_load_lds_dwordx4 v[138:139], off
	v_lshl_add_u64 v[138:139], s[10:11], 0, v[128:129]
	s_add_i32 m0, s12, 0x2000
	s_nop 0
	global_load_lds_dwordx4 v[138:139], off
	v_lshl_add_u64 v[138:139], v[212:213], 0, s[46:47]
	s_mov_b32 m0, s37
	s_nop 0
	global_load_lds_dwordx4 v[138:139], off
	v_lshl_add_u64 v[138:139], v[214:215], 0, s[46:47]
	s_mov_b32 m0, s38
	s_nop 0
	global_load_lds_dwordx4 v[138:139], off
	s_waitcnt vmcnt(8)
	s_waitcnt lgkmcnt(0)
	s_barrier
	s_waitcnt lgkmcnt(0)
	v_mfma_f32_16x16x32_bf16 v[60:63], v[144:147], v[176:179], v[60:63]
	v_mfma_f32_16x16x32_bf16 v[52:55], v[152:155], v[176:179], v[52:55]
	v_mfma_f32_16x16x32_bf16 v[44:47], v[144:147], v[184:187], v[44:47]
	v_mfma_f32_16x16x32_bf16 v[36:39], v[152:155], v[184:187], v[36:39]
	v_mfma_f32_16x16x32_bf16 v[28:31], v[144:147], v[192:195], v[28:31]
	v_mfma_f32_16x16x32_bf16 v[20:23], v[152:155], v[192:195], v[20:23]
	v_mfma_f32_16x16x32_bf16 v[12:15], v[144:147], v[200:203], v[12:15]
	v_mfma_f32_16x16x32_bf16 v[4:7], v[152:155], v[200:203], v[4:7]
	v_mfma_f32_16x16x32_bf16 v[60:63], v[148:151], v[180:183], v[60:63]
	v_mfma_f32_16x16x32_bf16 v[52:55], v[156:159], v[180:183], v[52:55]
	v_mfma_f32_16x16x32_bf16 v[44:47], v[148:151], v[188:191], v[44:47]
	v_mfma_f32_16x16x32_bf16 v[36:39], v[156:159], v[188:191], v[36:39]
	v_mfma_f32_16x16x32_bf16 v[28:31], v[148:151], v[196:199], v[28:31]
	v_mfma_f32_16x16x32_bf16 v[20:23], v[156:159], v[196:199], v[20:23]
	v_mfma_f32_16x16x32_bf16 v[12:15], v[148:151], v[204:207], v[12:15]
	v_mfma_f32_16x16x32_bf16 v[4:7], v[156:159], v[204:207], v[4:7]
	v_mfma_f32_16x16x32_bf16 v[56:59], v[160:163], v[176:179], v[56:59]
	v_mfma_f32_16x16x32_bf16 v[48:51], v[168:171], v[176:179], v[48:51]
	v_mfma_f32_16x16x32_bf16 v[40:43], v[160:163], v[184:187], v[40:43]
	v_mfma_f32_16x16x32_bf16 v[32:35], v[168:171], v[184:187], v[32:35]
	v_mfma_f32_16x16x32_bf16 v[24:27], v[160:163], v[192:195], v[24:27]
	v_mfma_f32_16x16x32_bf16 v[16:19], v[168:171], v[192:195], v[16:19]
	v_mfma_f32_16x16x32_bf16 v[8:11], v[160:163], v[200:203], v[8:11]
	v_mfma_f32_16x16x32_bf16 v[0:3], v[168:171], v[200:203], v[0:3]
	v_mfma_f32_16x16x32_bf16 v[56:59], v[164:167], v[180:183], v[56:59]
	v_mfma_f32_16x16x32_bf16 v[48:51], v[172:175], v[180:183], v[48:51]
	v_mfma_f32_16x16x32_bf16 v[40:43], v[164:167], v[188:191], v[40:43]
	v_mfma_f32_16x16x32_bf16 v[32:35], v[172:175], v[188:191], v[32:35]
	v_mfma_f32_16x16x32_bf16 v[24:27], v[164:167], v[196:199], v[24:27]
	v_mfma_f32_16x16x32_bf16 v[16:19], v[172:175], v[196:199], v[16:19]
	v_mfma_f32_16x16x32_bf16 v[8:11], v[164:167], v[204:207], v[8:11]
	v_mfma_f32_16x16x32_bf16 v[0:3], v[172:175], v[204:207], v[0:3]
	s_barrier
	s_add_i32 s52, s52, 2
	s_add_u32 s16, s16, 0x100
	s_addc_u32 s17, s17, 0
	s_add_u32 s44, s44, 0x100
	s_addc_u32 s45, s45, 0
	s_cmp_gt_u32 s52, 29
	s_cbranch_scc0 .LBB0_27
	s_and_b64 vcc, exec, s[18:19]
	s_cbranch_vccz .LBB0_30
	s_barrier

; #define PG8_STAGE(bufoff, gbase, voff) do { _Pragma("unroll") for (int _i = 0; _i < 2; ++_i) \
;         __builtin_amdgcn_global_load_lds((const unsigned*)((const char*)(gbase) + (voff)[_i]), (LAS unsigned*)(lds + (bufoff) + ldsw + _i * 8192), 16, 0, 0); } while (0)
; #define PG8_LDA(dst, b, h) do { _Pragma("unroll") for (int m = 0; m < 4; ++m) _Pragma("unroll") for (int k = 0; k < 2; ++k) dst[m][k] = *(const LAS bf16x8*)(lds + PG8_SA(b, h) + aoff + m * 2048 + k * 1024); } while (0)
; #define PG8_LDB(dst, b, h) do { _Pragma("unroll") for (int n = 0; n < 2; ++n) _Pragma("unroll") for (int k = 0; k < 2; ++k) dst[n][k] = *(const LAS bf16x8*)(lds + PG8_SB(b, h) + boff + n * 2048 + k * 1024); } while (0)
; #define PG8_MMA(ai, bj, At, Bt) do { __builtin_amdgcn_s_setprio(1); _Pragma("unroll") for (int m = 0; m < 4; ++m) _Pragma("unroll") for (int n = 0; n < 2; ++n) _Pragma("unroll") for (int k = 0; k < 2; ++k) \
;         acc[ai][bj][m][n] = __builtin_amdgcn_mfma_f32_16x16x32_bf16(Bt[n][k], At[m][k], acc[ai][bj][m][n], 0, 0, 0); __builtin_amdgcn_s_setprio(0); } while (0)
; #define PG8_WAIT_V(n) asm volatile("s_waitcnt vmcnt(" #n ")" ::: "memory")
; #define PG8_WAIT_L(n) asm volatile("s_waitcnt lgkmcnt(" #n ")" ::: "memory")
; #define PG8_BAR __builtin_amdgcn_s_barrier()
; template <class Epi, class Sched>
; __device__ __forceinline__ void gemm_phase(LAS unsigned char* lds, const Gemm g, const Sched& S, const Epi& E, const int wv) {
;     ...
;         for (int t = 0; t < nt; t += 2) {
;             const bool last = (t == nt - 2);
;             const char* a1 = cA + (size_t)(t + 1) * kstep;
;             const char* a2 = last ? nA : cA + (size_t)(t + 2) * kstep; const char* b2 = last ? nB : cB + (size_t)(t + 2) * kstep;
;             const char* a3 = a2 + kstep; const char* b3 = b2 + kstep;
;             if (last && has_next) S.a_ready(nxt);
;             PG8_LDB(B0, 0, 0); PG8_LDB(B1, 0, 1); PG8_SCHED; PG8_LDA(At, 0, 0); PG8_STAGE(PG8_SA(1, 1), a1 + hstep, voffA);
;             PG8_WAIT_V(8); PG8_WAIT_L(0); PG8_BAR; PG8_MMA(0, 0, At, B0); PG8_MMA(0, 1, At, B1); PG8_BAR; PG8_SCHED;
;             PG8_LDA(At, 0, 1); PG8_STAGE(PG8_SB(0, 0), b2, voffB); PG8_STAGE(PG8_SB(0, 1), b2 + hstep, voffB); PG8_STAGE(PG8_SA(0, 0), a2, voffA);
;             PG8_WAIT_V(8); PG8_WAIT_L(0); PG8_BAR; PG8_MMA(1, 0, At, B0); PG8_MMA(1, 1, At, B1); PG8_BAR; PG8_SCHED;
.LBB0_81:
	s_add_i32 s44, s10, 2
	s_add_u32 s45, s24, 0x80
	s_addc_u32 s11, s25, 0
	s_add_i32 s52, 0, 0x10000
	s_cmp_eq_u32 s36, s10
	s_cselect_b32 s11, s7, s11
	s_cselect_b32 s10, s6, s45
	v_add_u32_e32 v138, s52, v142
	s_cselect_b32 s83, s23, s13
	s_cselect_b32 s82, s22, s12
	s_add_i32 s45, 0, 0x14000
	ds_read_b128 v[146:149], v138
	ds_read_b128 v[150:153], v138 offset:1024
	ds_read_b128 v[154:157], v138 offset:2048
	ds_read_b128 v[158:161], v138 offset:3072
	v_add_u32_e32 v138, s45, v142
	ds_read_b128 v[162:165], v138
	ds_read_b128 v[166:169], v138 offset:1024
	ds_read_b128 v[170:173], v138 offset:2048
	ds_read_b128 v[174:177], v138 offset:3072
	v_lshl_add_u64 v[140:141], s[24:25], 0, v[134:135]
	s_add_i32 m0, s27, 0xc000
	ds_read_b128 v[178:181], v144
	ds_read_b128 v[182:185], v144 offset:1024
	ds_read_b128 v[186:189], v144 offset:2048
	ds_read_b128 v[190:193], v144 offset:3072
	ds_read_b128 v[194:197], v144 offset:4096
	ds_read_b128 v[198:201], v144 offset:5120
	ds_read_b128 v[202:205], v144 offset:6144
	ds_read_b128 v[206:209], v144 offset:7168
	global_load_lds_dwordx4 v[140:141], off
	v_lshl_add_u64 v[140:141], s[24:25], 0, v[136:137]
	s_add_i32 m0, s27, 0xe000
	s_nop 0
	global_load_lds_dwordx4 v[140:141], off
	s_waitcnt vmcnt(8)
	s_waitcnt lgkmcnt(0)
	s_barrier
	s_waitcnt lgkmcnt(0)
	v_mfma_f32_16x16x32_bf16 v[124:127], v[146:149], v[178:181], v[124:127]
	v_mfma_f32_16x16x32_bf16 v[120:123], v[154:157], v[178:181], v[120:123]
	v_mfma_f32_16x16x32_bf16 v[112:115], v[146:149], v[186:189], v[112:115]
	v_mfma_f32_16x16x32_bf16 v[104:107], v[154:157], v[186:189], v[104:107]
	v_mfma_f32_16x16x32_bf16 v[96:99], v[146:149], v[194:197], v[96:99]
	v_mfma_f32_16x16x32_bf16 v[88:91], v[154:157], v[194:197], v[88:91]
	v_mfma_f32_16x16x32_bf16 v[80:83], v[146:149], v[202:205], v[80:83]
	v_mfma_f32_16x16x32_bf16 v[72:75], v[154:157], v[202:205], v[72:75]
	v_mfma_f32_16x16x32_bf16 v[124:127], v[150:153], v[182:185], v[124:127]
	v_mfma_f32_16x16x32_bf16 v[120:123], v[158:161], v[182:185], v[120:123]
	v_mfma_f32_16x16x32_bf16 v[112:115], v[150:153], v[190:193], v[112:115]
	v_mfma_f32_16x16x32_bf16 v[104:107], v[158:161], v[190:193], v[104:107]
	v_mfma_f32_16x16x32_bf16 v[96:99], v[150:153], v[198:201], v[96:99]
	v_mfma_f32_16x16x32_bf16 v[88:91], v[158:161], v[198:201], v[88:91]
	v_mfma_f32_16x16x32_bf16 v[80:83], v[150:153], v[206:209], v[80:83]
	v_mfma_f32_16x16x32_bf16 v[72:75], v[158:161], v[206:209], v[72:75]
	v_mfma_f32_16x16x32_bf16 v[116:119], v[162:165], v[178:181], v[116:119]
	v_mfma_f32_16x16x32_bf16 v[108:111], v[170:173], v[178:181], v[108:111]
	v_mfma_f32_16x16x32_bf16 v[100:103], v[162:165], v[186:189], v[100:103]
	v_mfma_f32_16x16x32_bf16 v[92:95], v[170:173], v[186:189], v[92:95]
	v_mfma_f32_16x16x32_bf16 v[84:87], v[162:165], v[194:197], v[84:87]
	v_mfma_f32_16x16x32_bf16 v[76:79], v[170:173], v[194:197], v[76:79]
	v_mfma_f32_16x16x32_bf16 v[68:71], v[162:165], v[202:205], v[68:71]
	v_mfma_f32_16x16x32_bf16 v[64:67], v[170:173], v[202:205], v[64:67]
	v_mfma_f32_16x16x32_bf16 v[116:119], v[166:169], v[182:185], v[116:119]
	v_mfma_f32_16x16x32_bf16 v[108:111], v[174:177], v[182:185], v[108:111]
	v_mfma_f32_16x16x32_bf16 v[100:103], v[166:169], v[190:193], v[100:103]
	v_mfma_f32_16x16x32_bf16 v[92:95], v[174:177], v[190:193], v[92:95]
	v_mfma_f32_16x16x32_bf16 v[84:87], v[166:169], v[198:201], v[84:87]
	v_mfma_f32_16x16x32_bf16 v[76:79], v[174:177], v[198:201], v[76:79]
	v_mfma_f32_16x16x32_bf16 v[68:71], v[166:169], v[206:209], v[68:71]
	v_mfma_f32_16x16x32_bf16 v[64:67], v[174:177], v[206:209], v[64:67]
	s_barrier
	s_add_i32 s52, s52, s26
	v_lshl_add_u64 v[140:141], s[82:83], 0, v[210:211]
	s_mov_b32 m0, s52
	ds_read_b128 v[178:181], v144 offset:16384
	ds_read_b128 v[182:185], v144 offset:17408
	ds_read_b128 v[186:189], v144 offset:18432
	ds_read_b128 v[190:193], v144 offset:19456
	ds_read_b128 v[194:197], v144 offset:20480
	ds_read_b128 v[198:201], v144 offset:21504
	ds_read_b128 v[202:205], v144 offset:22528
	ds_read_b128 v[206:209], v144 offset:23552
	global_load_lds_dwordx4 v[140:141], off
	s_add_i32 m0, s52, 0x2000
	v_lshl_add_u64 v[212:213], s[82:83], 0, v[128:129]
	s_add_u32 s82, s82, s38
	s_addc_u32 s83, s83, 0
	s_add_i32 s45, s45, s26
	global_load_lds_dwordx4 v[212:213], off
	v_lshl_add_u64 v[214:215], s[82:83], 0, v[210:211]
	s_mov_b32 m0, s45
	v_lshl_add_u64 v[216:217], s[82:83], 0, v[128:129]
	global_load_lds_dwordx4 v[214:215], off
	s_add_i32 m0, s45, 0x2000
	v_lshl_add_u64 v[218:219], s[10:11], 0, v[132:133]
	global_load_lds_dwordx4 v[216:217], off
	s_mov_b32 m0, s27
	v_lshl_add_u64 v[220:221], s[10:11], 0, v[130:131]
	global_load_lds_dwordx4 v[218:219], off
	s_mov_b32 m0, s28
	s_nop 0
	global_load_lds_dwordx4 v[220:221], off
	s_waitcnt vmcnt(8)
	s_waitcnt lgkmcnt(0)
	s_barrier
; #define PG8_STAGE(bufoff, gbase, voff) do { _Pragma("unroll") for (int _i = 0; _i < 2; ++_i) \
;         __builtin_amdgcn_global_load_lds((const unsigned*)((const char*)(gbase) + (voff)[_i]), (LAS unsigned*)(lds + (bufoff) + ldsw + _i * 8192), 16, 0, 0); } while (0)
; #define PG8_LDA(dst, b, h) do { _Pragma("unroll") for (int m = 0; m < 4; ++m) _Pragma("unroll") for (int k = 0; k < 2; ++k) dst[m][k] = *(const LAS bf16x8*)(lds + PG8_SA(b, h) + aoff + m * 2048 + k * 1024); } while (0)
; #define PG8_LDB(dst, b, h) do { _Pragma("unroll") for (int n = 0; n < 2; ++n) _Pragma("unroll") for (int k = 0; k < 2; ++k) dst[n][k] = *(const LAS bf16x8*)(lds + PG8_SB(b, h) + boff + n * 2048 + k * 1024); } while (0)
; #define PG8_MMA(ai, bj, At, Bt) do { __builtin_amdgcn_s_setprio(1); _Pragma("unroll") for (int m = 0; m < 4; ++m) _Pragma("unroll") for (int n = 0; n < 2; ++n) _Pragma("unroll") for (int k = 0; k < 2; ++k) \
;         acc[ai][bj][m][n] = __builtin_amdgcn_mfma_f32_16x16x32_bf16(Bt[n][k], At[m][k], acc[ai][bj][m][n], 0, 0, 0); __builtin_amdgcn_s_setprio(0); } while (0)
; #define PG8_WAIT_V(n) asm volatile("s_waitcnt vmcnt(" #n ")" ::: "memory")
; #define PG8_WAIT_L(n) asm volatile("s_waitcnt lgkmcnt(" #n ")" ::: "memory")
; #define PG8_BAR __builtin_amdgcn_s_barrier()
; #define PG8_SCHED __builtin_amdgcn_sched_barrier(0)
; template <class Epi, class Sched>
; __device__ __forceinline__ void gemm_phase(LAS unsigned char* lds, const Gemm g, const Sched& S, const Epi& E, const int wv) {
;     ...
;             PG8_WAIT_V(8); PG8_WAIT_L(0); PG8_BAR; PG8_MMA(1, 0, At, B0); PG8_MMA(1, 1, At, B1); PG8_BAR; PG8_SCHED;
;             PG8_LDB(B0, 1, 0); PG8_LDB(B1, 1, 1); PG8_SCHED; PG8_LDA(At, 1, 0); PG8_STAGE(PG8_SA(0, 1), a2 + hstep, voffA);
;             PG8_WAIT_V(8); PG8_WAIT_L(0); PG8_BAR; PG8_MMA(0, 0, At, B0); PG8_MMA(0, 1, At, B1); PG8_BAR; PG8_SCHED;
	s_waitcnt lgkmcnt(0)
	v_mfma_f32_16x16x32_bf16 v[60:63], v[146:149], v[178:181], v[60:63]
	v_mfma_f32_16x16x32_bf16 v[56:59], v[154:157], v[178:181], v[56:59]
	v_mfma_f32_16x16x32_bf16 v[48:51], v[146:149], v[186:189], v[48:51]
	v_mfma_f32_16x16x32_bf16 v[40:43], v[154:157], v[186:189], v[40:43]
	v_mfma_f32_16x16x32_bf16 v[32:35], v[146:149], v[194:197], v[32:35]
	v_mfma_f32_16x16x32_bf16 v[24:27], v[154:157], v[194:197], v[24:27]
	v_mfma_f32_16x16x32_bf16 v[16:19], v[146:149], v[202:205], v[16:19]
	v_mfma_f32_16x16x32_bf16 v[8:11], v[154:157], v[202:205], v[8:11]
	v_mfma_f32_16x16x32_bf16 v[60:63], v[150:153], v[182:185], v[60:63]
	v_mfma_f32_16x16x32_bf16 v[56:59], v[158:161], v[182:185], v[56:59]
	v_mfma_f32_16x16x32_bf16 v[48:51], v[150:153], v[190:193], v[48:51]
	v_mfma_f32_16x16x32_bf16 v[40:43], v[158:161], v[190:193], v[40:43]
	v_mfma_f32_16x16x32_bf16 v[32:35], v[150:153], v[198:201], v[32:35]
	v_mfma_f32_16x16x32_bf16 v[24:27], v[158:161], v[198:201], v[24:27]
	v_mfma_f32_16x16x32_bf16 v[16:19], v[150:153], v[206:209], v[16:19]
	v_mfma_f32_16x16x32_bf16 v[8:11], v[158:161], v[206:209], v[8:11]
	v_mfma_f32_16x16x32_bf16 v[52:55], v[162:165], v[178:181], v[52:55]
	v_mfma_f32_16x16x32_bf16 v[44:47], v[170:173], v[178:181], v[44:47]
	v_mfma_f32_16x16x32_bf16 v[36:39], v[162:165], v[186:189], v[36:39]
	v_mfma_f32_16x16x32_bf16 v[28:31], v[170:173], v[186:189], v[28:31]
	v_mfma_f32_16x16x32_bf16 v[20:23], v[162:165], v[194:197], v[20:23]
	v_mfma_f32_16x16x32_bf16 v[12:15], v[170:173], v[194:197], v[12:15]
	v_mfma_f32_16x16x32_bf16 v[4:7], v[162:165], v[202:205], v[4:7]
	v_mfma_f32_16x16x32_bf16 v[0:3], v[170:173], v[202:205], v[0:3]
	v_mfma_f32_16x16x32_bf16 v[52:55], v[166:169], v[182:185], v[52:55]
	v_mfma_f32_16x16x32_bf16 v[44:47], v[174:177], v[182:185], v[44:47]
	v_mfma_f32_16x16x32_bf16 v[36:39], v[166:169], v[190:193], v[36:39]
	v_mfma_f32_16x16x32_bf16 v[28:31], v[174:177], v[190:193], v[28:31]
	v_mfma_f32_16x16x32_bf16 v[20:23], v[166:169], v[198:201], v[20:23]
	v_mfma_f32_16x16x32_bf16 v[12:15], v[174:177], v[198:201], v[12:15]
	v_mfma_f32_16x16x32_bf16 v[4:7], v[166:169], v[206:209], v[4:7]
	v_mfma_f32_16x16x32_bf16 v[0:3], v[174:177], v[206:209], v[0:3]
	s_barrier
	s_add_i32 s45, 0, 0x18000
	v_add_u32_e32 v138, s45, v142
	s_add_i32 s52, 0, 0x1c000
	ds_read_b128 v[146:149], v138
	ds_read_b128 v[150:153], v138 offset:1024
	ds_read_b128 v[154:157], v138 offset:2048
	ds_read_b128 v[158:161], v138 offset:3072
	v_add_u32_e32 v138, s52, v142
	ds_read_b128 v[162:165], v138
	ds_read_b128 v[166:169], v138 offset:1024
	ds_read_b128 v[170:173], v138 offset:2048
	ds_read_b128 v[174:177], v138 offset:3072
	s_add_u32 s10, s10, s38
	s_addc_u32 s11, s11, 0
	s_mov_b32 m0, s29
	v_lshl_add_u64 v[222:223], s[10:11], 0, v[132:133]
	ds_read_b128 v[178:181], v144 offset:32768
	ds_read_b128 v[182:185], v144 offset:33792
	ds_read_b128 v[186:189], v144 offset:34816
	ds_read_b128 v[190:193], v144 offset:35840
	ds_read_b128 v[194:197], v144 offset:36864
	ds_read_b128 v[198:201], v144 offset:37888
	ds_read_b128 v[202:205], v144 offset:38912
	ds_read_b128 v[206:209], v144 offset:39936
	global_load_lds_dwordx4 v[222:223], off
	v_lshl_add_u64 v[222:223], s[10:11], 0, v[130:131]
	s_mov_b32 m0, s30
	s_nop 0
	global_load_lds_dwordx4 v[222:223], off
	s_waitcnt vmcnt(8)
	s_waitcnt lgkmcnt(0)
	s_barrier
	s_waitcnt lgkmcnt(0)
	v_mfma_f32_16x16x32_bf16 v[124:127], v[146:149], v[178:181], v[124:127]
	v_mfma_f32_16x16x32_bf16 v[120:123], v[154:157], v[178:181], v[120:123]
	v_mfma_f32_16x16x32_bf16 v[112:115], v[146:149], v[186:189], v[112:115]
	v_mfma_f32_16x16x32_bf16 v[104:107], v[154:157], v[186:189], v[104:107]
	v_mfma_f32_16x16x32_bf16 v[96:99], v[146:149], v[194:197], v[96:99]
	v_mfma_f32_16x16x32_bf16 v[88:91], v[154:157], v[194:197], v[88:91]
	v_mfma_f32_16x16x32_bf16 v[80:83], v[146:149], v[202:205], v[80:83]
	v_mfma_f32_16x16x32_bf16 v[72:75], v[154:157], v[202:205], v[72:75]
	v_mfma_f32_16x16x32_bf16 v[124:127], v[150:153], v[182:185], v[124:127]
	v_mfma_f32_16x16x32_bf16 v[120:123], v[158:161], v[182:185], v[120:123]
	v_mfma_f32_16x16x32_bf16 v[112:115], v[150:153], v[190:193], v[112:115]
	v_mfma_f32_16x16x32_bf16 v[104:107], v[158:161], v[190:193], v[104:107]
	v_mfma_f32_16x16x32_bf16 v[96:99], v[150:153], v[198:201], v[96:99]
	v_mfma_f32_16x16x32_bf16 v[88:91], v[158:161], v[198:201], v[88:91]
	v_mfma_f32_16x16x32_bf16 v[80:83], v[150:153], v[206:209], v[80:83]
	v_mfma_f32_16x16x32_bf16 v[72:75], v[158:161], v[206:209], v[72:75]
	v_mfma_f32_16x16x32_bf16 v[116:119], v[162:165], v[178:181], v[116:119]
	v_mfma_f32_16x16x32_bf16 v[108:111], v[170:173], v[178:181], v[108:111]
	v_mfma_f32_16x16x32_bf16 v[100:103], v[162:165], v[186:189], v[100:103]
	v_mfma_f32_16x16x32_bf16 v[92:95], v[170:173], v[186:189], v[92:95]
	v_mfma_f32_16x16x32_bf16 v[84:87], v[162:165], v[194:197], v[84:87]
	v_mfma_f32_16x16x32_bf16 v[76:79], v[170:173], v[194:197], v[76:79]
	v_mfma_f32_16x16x32_bf16 v[68:71], v[162:165], v[202:205], v[68:71]
	v_mfma_f32_16x16x32_bf16 v[64:67], v[170:173], v[202:205], v[64:67]
	v_mfma_f32_16x16x32_bf16 v[116:119], v[166:169], v[182:185], v[116:119]
	v_mfma_f32_16x16x32_bf16 v[108:111], v[174:177], v[182:185], v[108:111]
	v_mfma_f32_16x16x32_bf16 v[100:103], v[166:169], v[190:193], v[100:103]
	v_mfma_f32_16x16x32_bf16 v[92:95], v[174:177], v[190:193], v[92:95]
	v_mfma_f32_16x16x32_bf16 v[84:87], v[166:169], v[198:201], v[84:87]
	v_mfma_f32_16x16x32_bf16 v[76:79], v[174:177], v[198:201], v[76:79]
	v_mfma_f32_16x16x32_bf16 v[68:71], v[166:169], v[206:209], v[68:71]
	v_mfma_f32_16x16x32_bf16 v[64:67], v[174:177], v[206:209], v[64:67]
	s_barrier
; #define PG8_STAGE(bufoff, gbase, voff) do { _Pragma("unroll") for (int _i = 0; _i < 2; ++_i) \
;         __builtin_amdgcn_global_load_lds((const unsigned*)((const char*)(gbase) + (voff)[_i]), (LAS unsigned*)(lds + (bufoff) + ldsw + _i * 8192), 16, 0, 0); } while (0)
; #define PG8_LDA(dst, b, h) do { _Pragma("unroll") for (int m = 0; m < 4; ++m) _Pragma("unroll") for (int k = 0; k < 2; ++k) dst[m][k] = *(const LAS bf16x8*)(lds + PG8_SA(b, h) + aoff + m * 2048 + k * 1024); } while (0)
; #define PG8_MMA(ai, bj, At, Bt) do { __builtin_amdgcn_s_setprio(1); _Pragma("unroll") for (int m = 0; m < 4; ++m) _Pragma("unroll") for (int n = 0; n < 2; ++n) _Pragma("unroll") for (int k = 0; k < 2; ++k) \
;         acc[ai][bj][m][n] = __builtin_amdgcn_mfma_f32_16x16x32_bf16(Bt[n][k], At[m][k], acc[ai][bj][m][n], 0, 0, 0); __builtin_amdgcn_s_setprio(0); } while (0)
; #define PG8_WAIT_V(n) asm volatile("s_waitcnt vmcnt(" #n ")" ::: "memory")
; #define PG8_WAIT_L(n) asm volatile("s_waitcnt lgkmcnt(" #n ")" ::: "memory")
; #define PG8_BAR __builtin_amdgcn_s_barrier()
; #define PG8_SCHED __builtin_amdgcn_sched_barrier(0)
; template <class Epi, class Sched>
; __device__ __forceinline__ void gemm_phase(LAS unsigned char* lds, const Gemm g, const Sched& S, const Epi& E, const int wv) {
;     ...
;             PG8_LDA(At, 1, 1); PG8_STAGE(PG8_SB(1, 0), b3, voffB); PG8_STAGE(PG8_SB(1, 1), b3 + hstep, voffB); PG8_STAGE(PG8_SA(1, 0), a3, voffA);
;             PG8_WAIT_V(8); PG8_WAIT_L(0); PG8_BAR; PG8_MMA(1, 0, At, B0); PG8_MMA(1, 1, At, B1); PG8_BAR; PG8_SCHED;
;         }
;         if (wr == 0) PG8_BAR;
	s_add_i32 s10, s45, s26
	v_lshl_add_u64 v[140:141], v[140:141], 0, s[46:47]
	s_mov_b32 m0, s10
	ds_read_b128 v[178:181], v144 offset:49152
	ds_read_b128 v[182:185], v144 offset:50176
	ds_read_b128 v[186:189], v144 offset:51200
	ds_read_b128 v[190:193], v144 offset:52224
	ds_read_b128 v[194:197], v144 offset:53248
	ds_read_b128 v[198:201], v144 offset:54272
	ds_read_b128 v[202:205], v144 offset:55296
	ds_read_b128 v[206:209], v144 offset:56320
	global_load_lds_dwordx4 v[140:141], off
	v_lshl_add_u64 v[140:141], v[212:213], 0, s[46:47]
	s_add_i32 m0, s10, 0x2000
	s_add_i32 s10, s52, s26
	global_load_lds_dwordx4 v[140:141], off
	v_lshl_add_u64 v[140:141], v[214:215], 0, s[46:47]
	s_mov_b32 m0, s10
	s_nop 0
	global_load_lds_dwordx4 v[140:141], off
	v_lshl_add_u64 v[140:141], v[216:217], 0, s[46:47]
	s_add_i32 m0, s10, 0x2000
	s_nop 0
	global_load_lds_dwordx4 v[140:141], off
	v_lshl_add_u64 v[140:141], v[218:219], 0, s[46:47]
	s_mov_b32 m0, s34
	s_nop 0
	global_load_lds_dwordx4 v[140:141], off
	v_lshl_add_u64 v[140:141], v[220:221], 0, s[46:47]
	s_mov_b32 m0, s35
	s_nop 0
	global_load_lds_dwordx4 v[140:141], off
	s_waitcnt vmcnt(8)
	s_waitcnt lgkmcnt(0)
	s_barrier
	s_waitcnt lgkmcnt(0)
	v_mfma_f32_16x16x32_bf16 v[60:63], v[146:149], v[178:181], v[60:63]
	v_mfma_f32_16x16x32_bf16 v[56:59], v[154:157], v[178:181], v[56:59]
	v_mfma_f32_16x16x32_bf16 v[48:51], v[146:149], v[186:189], v[48:51]
	v_mfma_f32_16x16x32_bf16 v[40:43], v[154:157], v[186:189], v[40:43]
	v_mfma_f32_16x16x32_bf16 v[32:35], v[146:149], v[194:197], v[32:35]
	v_mfma_f32_16x16x32_bf16 v[24:27], v[154:157], v[194:197], v[24:27]
	v_mfma_f32_16x16x32_bf16 v[16:19], v[146:149], v[202:205], v[16:19]
	v_mfma_f32_16x16x32_bf16 v[8:11], v[154:157], v[202:205], v[8:11]
	v_mfma_f32_16x16x32_bf16 v[60:63], v[150:153], v[182:185], v[60:63]
	v_mfma_f32_16x16x32_bf16 v[56:59], v[158:161], v[182:185], v[56:59]
	v_mfma_f32_16x16x32_bf16 v[48:51], v[150:153], v[190:193], v[48:51]
	v_mfma_f32_16x16x32_bf16 v[40:43], v[158:161], v[190:193], v[40:43]
	v_mfma_f32_16x16x32_bf16 v[32:35], v[150:153], v[198:201], v[32:35]
	v_mfma_f32_16x16x32_bf16 v[24:27], v[158:161], v[198:201], v[24:27]
	v_mfma_f32_16x16x32_bf16 v[16:19], v[150:153], v[206:209], v[16:19]
	v_mfma_f32_16x16x32_bf16 v[8:11], v[158:161], v[206:209], v[8:11]
	v_mfma_f32_16x16x32_bf16 v[52:55], v[162:165], v[178:181], v[52:55]
	v_mfma_f32_16x16x32_bf16 v[44:47], v[170:173], v[178:181], v[44:47]
	v_mfma_f32_16x16x32_bf16 v[36:39], v[162:165], v[186:189], v[36:39]
	v_mfma_f32_16x16x32_bf16 v[28:31], v[170:173], v[186:189], v[28:31]
	v_mfma_f32_16x16x32_bf16 v[20:23], v[162:165], v[194:197], v[20:23]
	v_mfma_f32_16x16x32_bf16 v[12:15], v[170:173], v[194:197], v[12:15]
	v_mfma_f32_16x16x32_bf16 v[4:7], v[162:165], v[202:205], v[4:7]
	v_mfma_f32_16x16x32_bf16 v[0:3], v[170:173], v[202:205], v[0:3]
	v_mfma_f32_16x16x32_bf16 v[52:55], v[166:169], v[182:185], v[52:55]
	v_mfma_f32_16x16x32_bf16 v[44:47], v[174:177], v[182:185], v[44:47]
	v_mfma_f32_16x16x32_bf16 v[36:39], v[166:169], v[190:193], v[36:39]
	v_mfma_f32_16x16x32_bf16 v[28:31], v[174:177], v[190:193], v[28:31]
	v_mfma_f32_16x16x32_bf16 v[20:23], v[166:169], v[198:201], v[20:23]
	v_mfma_f32_16x16x32_bf16 v[12:15], v[174:177], v[198:201], v[12:15]
	v_mfma_f32_16x16x32_bf16 v[4:7], v[166:169], v[206:209], v[4:7]
	v_mfma_f32_16x16x32_bf16 v[0:3], v[174:177], v[206:209], v[0:3]
	s_barrier
	s_add_u32 s24, s24, 0x100
	s_addc_u32 s25, s25, 0
	s_add_u32 s12, s12, 0x100
	s_addc_u32 s13, s13, 0
	s_cmp_ge_u32 s44, s31
	s_mov_b32 s10, s44
	s_cbranch_scc0 .LBB0_81
	s_and_b64 vcc, exec, s[20:21]
	s_cbranch_vccz .LBB0_84
	s_barrier

; #define PG8_STAGE(bufoff, gbase, voff) do { _Pragma("unroll") for (int _i = 0; _i < 2; ++_i) \
;         __builtin_amdgcn_global_load_lds((const unsigned*)((const char*)(gbase) + (voff)[_i]), (LAS unsigned*)(lds + (bufoff) + ldsw + _i * 8192), 16, 0, 0); } while (0)
; #define PG8_LDA(dst, b, h) do { _Pragma("unroll") for (int m = 0; m < 4; ++m) _Pragma("unroll") for (int k = 0; k < 2; ++k) dst[m][k] = *(const LAS bf16x8*)(lds + PG8_SA(b, h) + aoff + m * 2048 + k * 1024); } while (0)
; #define PG8_LDB(dst, b, h) do { _Pragma("unroll") for (int n = 0; n < 2; ++n) _Pragma("unroll") for (int k = 0; k < 2; ++k) dst[n][k] = *(const LAS bf16x8*)(lds + PG8_SB(b, h) + boff + n * 2048 + k * 1024); } while (0)
; #define PG8_MMA(ai, bj, At, Bt) do { __builtin_amdgcn_s_setprio(1); _Pragma("unroll") for (int m = 0; m < 4; ++m) _Pragma("unroll") for (int n = 0; n < 2; ++n) _Pragma("unroll") for (int k = 0; k < 2; ++k) \
;         acc[ai][bj][m][n] = __builtin_amdgcn_mfma_f32_16x16x32_bf16(Bt[n][k], At[m][k], acc[ai][bj][m][n], 0, 0, 0); __builtin_amdgcn_s_setprio(0); } while (0)
; #define PG8_WAIT_V(n) asm volatile("s_waitcnt vmcnt(" #n ")" ::: "memory")
; #define PG8_WAIT_L(n) asm volatile("s_waitcnt lgkmcnt(" #n ")" ::: "memory")
; #define PG8_BAR __builtin_amdgcn_s_barrier()
; template <class Epi, class Sched>
; __device__ __forceinline__ void gemm_phase(LAS unsigned char* lds, const Gemm g, const Sched& S, const Epi& E, const int wv) {
;     ...
;         for (int t = 0; t < nt; t += 2) {
;             const bool last = (t == nt - 2);
;             const char* a1 = cA + (size_t)(t + 1) * kstep;
;             const char* a2 = last ? nA : cA + (size_t)(t + 2) * kstep; const char* b2 = last ? nB : cB + (size_t)(t + 2) * kstep;
;             const char* a3 = a2 + kstep; const char* b3 = b2 + kstep;
;             if (last && has_next) S.a_ready(nxt);
;             PG8_LDB(B0, 0, 0); PG8_LDB(B1, 0, 1); PG8_SCHED; PG8_LDA(At, 0, 0); PG8_STAGE(PG8_SA(1, 1), a1 + hstep, voffA);
;             PG8_WAIT_V(8); PG8_WAIT_L(0); PG8_BAR; PG8_MMA(0, 0, At, B0); PG8_MMA(0, 1, At, B1); PG8_BAR; PG8_SCHED;
;             PG8_LDA(At, 0, 1); PG8_STAGE(PG8_SB(0, 0), b2, voffB); PG8_STAGE(PG8_SB(0, 1), b2 + hstep, voffB); PG8_STAGE(PG8_SA(0, 0), a2, voffA);
;             PG8_WAIT_V(8); PG8_WAIT_L(0); PG8_BAR; PG8_MMA(1, 0, At, B0); PG8_MMA(1, 1, At, B1); PG8_BAR; PG8_SCHED;
.LBB0_324:
	s_add_u32 s10, s22, 0xfff80080
	s_addc_u32 s11, s23, -1
	s_add_i32 s43, 0, 0x10000
	s_cmp_eq_u32 s42, 28
	s_cselect_b32 s13, s17, s11
	s_cselect_b32 s12, s37, s10
	v_add_u32_e32 v138, s43, v144
	s_cselect_b32 s11, s15, s41
	s_cselect_b32 s10, s38, s40
	s_add_i32 s52, 0, 0x14000
	ds_read_b128 v[140:143], v138
	ds_read_b128 v[148:151], v138 offset:1024
	ds_read_b128 v[152:155], v138 offset:2048
	ds_read_b128 v[156:159], v138 offset:3072
	v_add_u32_e32 v138, s52, v144
	ds_read_b128 v[160:163], v138
	ds_read_b128 v[164:167], v138 offset:1024
	ds_read_b128 v[168:171], v138 offset:2048
	ds_read_b128 v[172:175], v138 offset:3072
	v_lshl_add_u64 v[208:209], s[22:23], 0, v[134:135]
	s_add_i32 m0, s26, 0xc000
	ds_read_b128 v[176:179], v146
	ds_read_b128 v[180:183], v146 offset:1024
	ds_read_b128 v[184:187], v146 offset:2048
	ds_read_b128 v[188:191], v146 offset:3072
	ds_read_b128 v[192:195], v146 offset:4096
	ds_read_b128 v[196:199], v146 offset:5120
	ds_read_b128 v[200:203], v146 offset:6144
	ds_read_b128 v[204:207], v146 offset:7168
	global_load_lds_dwordx4 v[208:209], off
	v_lshl_add_u64 v[208:209], s[22:23], 0, v[136:137]
	s_add_i32 m0, s26, 0xe000
	s_nop 0
	global_load_lds_dwordx4 v[208:209], off
	s_waitcnt vmcnt(8)
	s_waitcnt lgkmcnt(0)
	s_barrier
	s_waitcnt lgkmcnt(0)
	v_mfma_f32_16x16x32_bf16 v[124:127], v[140:143], v[176:179], v[124:127]
	v_mfma_f32_16x16x32_bf16 v[120:123], v[152:155], v[176:179], v[120:123]
	v_mfma_f32_16x16x32_bf16 v[112:115], v[140:143], v[184:187], v[112:115]
	v_mfma_f32_16x16x32_bf16 v[104:107], v[152:155], v[184:187], v[104:107]
	v_mfma_f32_16x16x32_bf16 v[96:99], v[140:143], v[192:195], v[96:99]
	v_mfma_f32_16x16x32_bf16 v[88:91], v[152:155], v[192:195], v[88:91]
	v_mfma_f32_16x16x32_bf16 v[80:83], v[140:143], v[200:203], v[80:83]
	v_mfma_f32_16x16x32_bf16 v[72:75], v[152:155], v[200:203], v[72:75]
	v_mfma_f32_16x16x32_bf16 v[124:127], v[148:151], v[180:183], v[124:127]
	v_mfma_f32_16x16x32_bf16 v[120:123], v[156:159], v[180:183], v[120:123]
	v_mfma_f32_16x16x32_bf16 v[112:115], v[148:151], v[188:191], v[112:115]
	v_mfma_f32_16x16x32_bf16 v[104:107], v[156:159], v[188:191], v[104:107]
	v_mfma_f32_16x16x32_bf16 v[96:99], v[148:151], v[196:199], v[96:99]
	v_mfma_f32_16x16x32_bf16 v[88:91], v[156:159], v[196:199], v[88:91]
	v_mfma_f32_16x16x32_bf16 v[80:83], v[148:151], v[204:207], v[80:83]
	v_mfma_f32_16x16x32_bf16 v[72:75], v[156:159], v[204:207], v[72:75]
	v_mfma_f32_16x16x32_bf16 v[116:119], v[160:163], v[176:179], v[116:119]
	v_mfma_f32_16x16x32_bf16 v[108:111], v[168:171], v[176:179], v[108:111]
	v_mfma_f32_16x16x32_bf16 v[100:103], v[160:163], v[184:187], v[100:103]
	v_mfma_f32_16x16x32_bf16 v[92:95], v[168:171], v[184:187], v[92:95]
	v_mfma_f32_16x16x32_bf16 v[84:87], v[160:163], v[192:195], v[84:87]
	v_mfma_f32_16x16x32_bf16 v[76:79], v[168:171], v[192:195], v[76:79]
	v_mfma_f32_16x16x32_bf16 v[68:71], v[160:163], v[200:203], v[68:71]
	v_mfma_f32_16x16x32_bf16 v[64:67], v[168:171], v[200:203], v[64:67]
	v_mfma_f32_16x16x32_bf16 v[116:119], v[164:167], v[180:183], v[116:119]
	v_mfma_f32_16x16x32_bf16 v[108:111], v[172:175], v[180:183], v[108:111]
	v_mfma_f32_16x16x32_bf16 v[100:103], v[164:167], v[188:191], v[100:103]
	v_mfma_f32_16x16x32_bf16 v[92:95], v[172:175], v[188:191], v[92:95]
	v_mfma_f32_16x16x32_bf16 v[84:87], v[164:167], v[196:199], v[84:87]
	v_mfma_f32_16x16x32_bf16 v[76:79], v[172:175], v[196:199], v[76:79]
	v_mfma_f32_16x16x32_bf16 v[68:71], v[164:167], v[204:207], v[68:71]
	v_mfma_f32_16x16x32_bf16 v[64:67], v[172:175], v[204:207], v[64:67]
	s_barrier
	s_add_i32 s43, s43, s25
	v_lshl_add_u64 v[208:209], s[10:11], 0, v[210:211]
	s_mov_b32 m0, s43
	ds_read_b128 v[176:179], v146 offset:16384
	ds_read_b128 v[180:183], v146 offset:17408
	ds_read_b128 v[184:187], v146 offset:18432
	ds_read_b128 v[188:191], v146 offset:19456
	ds_read_b128 v[192:195], v146 offset:20480
	ds_read_b128 v[196:199], v146 offset:21504
	ds_read_b128 v[200:203], v146 offset:22528
	ds_read_b128 v[204:207], v146 offset:23552
	global_load_lds_dwordx4 v[208:209], off
	s_add_i32 m0, s43, 0x2000
	s_add_u32 s44, s10, 0x80000
	v_lshl_add_u64 v[212:213], s[10:11], 0, v[128:129]
	s_addc_u32 s45, s11, 0
	s_add_i32 s43, s52, s25
	global_load_lds_dwordx4 v[212:213], off
	v_lshl_add_u64 v[214:215], s[44:45], 0, v[210:211]
	s_mov_b32 m0, s43
	v_lshl_add_u64 v[216:217], s[12:13], 0, v[130:131]
	global_load_lds_dwordx4 v[214:215], off
	v_lshl_add_u64 v[214:215], s[44:45], 0, v[128:129]
	s_add_i32 m0, s43, 0x2000
	s_nop 0
	global_load_lds_dwordx4 v[214:215], off
	v_lshl_add_u64 v[214:215], s[12:13], 0, v[132:133]
	s_mov_b32 m0, s26
	s_nop 0
	global_load_lds_dwordx4 v[214:215], off
	s_mov_b32 m0, s27
	s_nop 0
	global_load_lds_dwordx4 v[216:217], off
	s_waitcnt vmcnt(8)
	s_waitcnt lgkmcnt(0)
	s_barrier
; #define PG8_STAGE(bufoff, gbase, voff) do { _Pragma("unroll") for (int _i = 0; _i < 2; ++_i) \
;         __builtin_amdgcn_global_load_lds((const unsigned*)((const char*)(gbase) + (voff)[_i]), (LAS unsigned*)(lds + (bufoff) + ldsw + _i * 8192), 16, 0, 0); } while (0)
; #define PG8_LDA(dst, b, h) do { _Pragma("unroll") for (int m = 0; m < 4; ++m) _Pragma("unroll") for (int k = 0; k < 2; ++k) dst[m][k] = *(const LAS bf16x8*)(lds + PG8_SA(b, h) + aoff + m * 2048 + k * 1024); } while (0)
; #define PG8_LDB(dst, b, h) do { _Pragma("unroll") for (int n = 0; n < 2; ++n) _Pragma("unroll") for (int k = 0; k < 2; ++k) dst[n][k] = *(const LAS bf16x8*)(lds + PG8_SB(b, h) + boff + n * 2048 + k * 1024); } while (0)
; #define PG8_MMA(ai, bj, At, Bt) do { __builtin_amdgcn_s_setprio(1); _Pragma("unroll") for (int m = 0; m < 4; ++m) _Pragma("unroll") for (int n = 0; n < 2; ++n) _Pragma("unroll") for (int k = 0; k < 2; ++k) \
;         acc[ai][bj][m][n] = __builtin_amdgcn_mfma_f32_16x16x32_bf16(Bt[n][k], At[m][k], acc[ai][bj][m][n], 0, 0, 0); __builtin_amdgcn_s_setprio(0); } while (0)
; #define PG8_WAIT_V(n) asm volatile("s_waitcnt vmcnt(" #n ")" ::: "memory")
; #define PG8_WAIT_L(n) asm volatile("s_waitcnt lgkmcnt(" #n ")" ::: "memory")
; #define PG8_BAR __builtin_amdgcn_s_barrier()
; #define PG8_SCHED __builtin_amdgcn_sched_barrier(0)
; template <class Epi, class Sched>
; __device__ __forceinline__ void gemm_phase(LAS unsigned char* lds, const Gemm g, const Sched& S, const Epi& E, const int wv) {
;     ...
;             PG8_WAIT_V(8); PG8_WAIT_L(0); PG8_BAR; PG8_MMA(1, 0, At, B0); PG8_MMA(1, 1, At, B1); PG8_BAR; PG8_SCHED;
;             PG8_LDB(B0, 1, 0); PG8_LDB(B1, 1, 1); PG8_SCHED; PG8_LDA(At, 1, 0); PG8_STAGE(PG8_SA(0, 1), a2 + hstep, voffA);
;             PG8_WAIT_V(8); PG8_WAIT_L(0); PG8_BAR; PG8_MMA(0, 0, At, B0); PG8_MMA(0, 1, At, B1); PG8_BAR; PG8_SCHED;
	s_waitcnt lgkmcnt(0)
	v_mfma_f32_16x16x32_bf16 v[60:63], v[140:143], v[176:179], v[60:63]
	v_mfma_f32_16x16x32_bf16 v[56:59], v[152:155], v[176:179], v[56:59]
	v_mfma_f32_16x16x32_bf16 v[48:51], v[140:143], v[184:187], v[48:51]
	v_mfma_f32_16x16x32_bf16 v[40:43], v[152:155], v[184:187], v[40:43]
	v_mfma_f32_16x16x32_bf16 v[32:35], v[140:143], v[192:195], v[32:35]
	v_mfma_f32_16x16x32_bf16 v[24:27], v[152:155], v[192:195], v[24:27]
	v_mfma_f32_16x16x32_bf16 v[16:19], v[140:143], v[200:203], v[16:19]
	v_mfma_f32_16x16x32_bf16 v[8:11], v[152:155], v[200:203], v[8:11]
	v_mfma_f32_16x16x32_bf16 v[60:63], v[148:151], v[180:183], v[60:63]
	v_mfma_f32_16x16x32_bf16 v[56:59], v[156:159], v[180:183], v[56:59]
	v_mfma_f32_16x16x32_bf16 v[48:51], v[148:151], v[188:191], v[48:51]
	v_mfma_f32_16x16x32_bf16 v[40:43], v[156:159], v[188:191], v[40:43]
	v_mfma_f32_16x16x32_bf16 v[32:35], v[148:151], v[196:199], v[32:35]
	v_mfma_f32_16x16x32_bf16 v[24:27], v[156:159], v[196:199], v[24:27]
	v_mfma_f32_16x16x32_bf16 v[16:19], v[148:151], v[204:207], v[16:19]
	v_mfma_f32_16x16x32_bf16 v[8:11], v[156:159], v[204:207], v[8:11]
	v_mfma_f32_16x16x32_bf16 v[52:55], v[160:163], v[176:179], v[52:55]
	v_mfma_f32_16x16x32_bf16 v[44:47], v[168:171], v[176:179], v[44:47]
	v_mfma_f32_16x16x32_bf16 v[36:39], v[160:163], v[184:187], v[36:39]
	v_mfma_f32_16x16x32_bf16 v[28:31], v[168:171], v[184:187], v[28:31]
	v_mfma_f32_16x16x32_bf16 v[20:23], v[160:163], v[192:195], v[20:23]
	v_mfma_f32_16x16x32_bf16 v[12:15], v[168:171], v[192:195], v[12:15]
	v_mfma_f32_16x16x32_bf16 v[4:7], v[160:163], v[200:203], v[4:7]
	v_mfma_f32_16x16x32_bf16 v[0:3], v[168:171], v[200:203], v[0:3]
	v_mfma_f32_16x16x32_bf16 v[52:55], v[164:167], v[180:183], v[52:55]
	v_mfma_f32_16x16x32_bf16 v[44:47], v[172:175], v[180:183], v[44:47]
	v_mfma_f32_16x16x32_bf16 v[36:39], v[164:167], v[188:191], v[36:39]
	v_mfma_f32_16x16x32_bf16 v[28:31], v[172:175], v[188:191], v[28:31]
	v_mfma_f32_16x16x32_bf16 v[20:23], v[164:167], v[196:199], v[20:23]
	v_mfma_f32_16x16x32_bf16 v[12:15], v[172:175], v[196:199], v[12:15]
	v_mfma_f32_16x16x32_bf16 v[4:7], v[164:167], v[204:207], v[4:7]
	v_mfma_f32_16x16x32_bf16 v[0:3], v[172:175], v[204:207], v[0:3]
	s_barrier
	s_add_i32 s43, 0, 0x18000
	v_add_u32_e32 v138, s43, v144
	s_add_i32 s44, 0, 0x1c000
	ds_read_b128 v[140:143], v138
	ds_read_b128 v[148:151], v138 offset:1024
	ds_read_b128 v[152:155], v138 offset:2048
	ds_read_b128 v[156:159], v138 offset:3072
	v_add_u32_e32 v138, s44, v144
	ds_read_b128 v[160:163], v138
	ds_read_b128 v[164:167], v138 offset:1024
	ds_read_b128 v[168:171], v138 offset:2048
	ds_read_b128 v[172:175], v138 offset:3072
	s_add_u32 s12, s12, 0x80000
	s_addc_u32 s13, s13, 0
	s_mov_b32 m0, s28
	v_lshl_add_u64 v[218:219], s[12:13], 0, v[132:133]
	ds_read_b128 v[176:179], v146 offset:32768
	ds_read_b128 v[180:183], v146 offset:33792
	ds_read_b128 v[184:187], v146 offset:34816
	ds_read_b128 v[188:191], v146 offset:35840
	ds_read_b128 v[192:195], v146 offset:36864
	ds_read_b128 v[196:199], v146 offset:37888
	ds_read_b128 v[200:203], v146 offset:38912
	ds_read_b128 v[204:207], v146 offset:39936
	global_load_lds_dwordx4 v[218:219], off
	v_lshl_add_u64 v[218:219], s[12:13], 0, v[130:131]
	s_mov_b32 m0, s29
	s_nop 0
	global_load_lds_dwordx4 v[218:219], off
	s_waitcnt vmcnt(8)
	s_waitcnt lgkmcnt(0)
	s_barrier
	s_waitcnt lgkmcnt(0)
	v_mfma_f32_16x16x32_bf16 v[124:127], v[140:143], v[176:179], v[124:127]
	v_mfma_f32_16x16x32_bf16 v[120:123], v[152:155], v[176:179], v[120:123]
	v_mfma_f32_16x16x32_bf16 v[112:115], v[140:143], v[184:187], v[112:115]
	v_mfma_f32_16x16x32_bf16 v[104:107], v[152:155], v[184:187], v[104:107]
	v_mfma_f32_16x16x32_bf16 v[96:99], v[140:143], v[192:195], v[96:99]
	v_mfma_f32_16x16x32_bf16 v[88:91], v[152:155], v[192:195], v[88:91]
	v_mfma_f32_16x16x32_bf16 v[80:83], v[140:143], v[200:203], v[80:83]
	v_mfma_f32_16x16x32_bf16 v[72:75], v[152:155], v[200:203], v[72:75]
	v_mfma_f32_16x16x32_bf16 v[124:127], v[148:151], v[180:183], v[124:127]
	v_mfma_f32_16x16x32_bf16 v[120:123], v[156:159], v[180:183], v[120:123]
	v_mfma_f32_16x16x32_bf16 v[112:115], v[148:151], v[188:191], v[112:115]
	v_mfma_f32_16x16x32_bf16 v[104:107], v[156:159], v[188:191], v[104:107]
	v_mfma_f32_16x16x32_bf16 v[96:99], v[148:151], v[196:199], v[96:99]
	v_mfma_f32_16x16x32_bf16 v[88:91], v[156:159], v[196:199], v[88:91]
	v_mfma_f32_16x16x32_bf16 v[80:83], v[148:151], v[204:207], v[80:83]
	v_mfma_f32_16x16x32_bf16 v[72:75], v[156:159], v[204:207], v[72:75]
	v_mfma_f32_16x16x32_bf16 v[116:119], v[160:163], v[176:179], v[116:119]
	v_mfma_f32_16x16x32_bf16 v[108:111], v[168:171], v[176:179], v[108:111]
	v_mfma_f32_16x16x32_bf16 v[100:103], v[160:163], v[184:187], v[100:103]
	v_mfma_f32_16x16x32_bf16 v[92:95], v[168:171], v[184:187], v[92:95]
	v_mfma_f32_16x16x32_bf16 v[84:87], v[160:163], v[192:195], v[84:87]
	v_mfma_f32_16x16x32_bf16 v[76:79], v[168:171], v[192:195], v[76:79]
	v_mfma_f32_16x16x32_bf16 v[68:71], v[160:163], v[200:203], v[68:71]
	v_mfma_f32_16x16x32_bf16 v[64:67], v[168:171], v[200:203], v[64:67]
	v_mfma_f32_16x16x32_bf16 v[116:119], v[164:167], v[180:183], v[116:119]
	v_mfma_f32_16x16x32_bf16 v[108:111], v[172:175], v[180:183], v[108:111]
	v_mfma_f32_16x16x32_bf16 v[100:103], v[164:167], v[188:191], v[100:103]
	v_mfma_f32_16x16x32_bf16 v[92:95], v[172:175], v[188:191], v[92:95]
	v_mfma_f32_16x16x32_bf16 v[84:87], v[164:167], v[196:199], v[84:87]
	v_mfma_f32_16x16x32_bf16 v[76:79], v[172:175], v[196:199], v[76:79]
	v_mfma_f32_16x16x32_bf16 v[68:71], v[164:167], v[204:207], v[68:71]
	v_mfma_f32_16x16x32_bf16 v[64:67], v[172:175], v[204:207], v[64:67]
	s_barrier
; #define PG8_STAGE(bufoff, gbase, voff) do { _Pragma("unroll") for (int _i = 0; _i < 2; ++_i) \
;         __builtin_amdgcn_global_load_lds((const unsigned*)((const char*)(gbase) + (voff)[_i]), (LAS unsigned*)(lds + (bufoff) + ldsw + _i * 8192), 16, 0, 0); } while (0)
; #define PG8_LDA(dst, b, h) do { _Pragma("unroll") for (int m = 0; m < 4; ++m) _Pragma("unroll") for (int k = 0; k < 2; ++k) dst[m][k] = *(const LAS bf16x8*)(lds + PG8_SA(b, h) + aoff + m * 2048 + k * 1024); } while (0)
; #define PG8_MMA(ai, bj, At, Bt) do { __builtin_amdgcn_s_setprio(1); _Pragma("unroll") for (int m = 0; m < 4; ++m) _Pragma("unroll") for (int n = 0; n < 2; ++n) _Pragma("unroll") for (int k = 0; k < 2; ++k) \
;         acc[ai][bj][m][n] = __builtin_amdgcn_mfma_f32_16x16x32_bf16(Bt[n][k], At[m][k], acc[ai][bj][m][n], 0, 0, 0); __builtin_amdgcn_s_setprio(0); } while (0)
; #define PG8_WAIT_V(n) asm volatile("s_waitcnt vmcnt(" #n ")" ::: "memory")
; #define PG8_WAIT_L(n) asm volatile("s_waitcnt lgkmcnt(" #n ")" ::: "memory")
; #define PG8_BAR __builtin_amdgcn_s_barrier()
; #define PG8_SCHED __builtin_amdgcn_sched_barrier(0)
; template <class Epi, class Sched>
; __device__ __forceinline__ void gemm_phase(LAS unsigned char* lds, const Gemm g, const Sched& S, const Epi& E, const int wv) {
;     ...
;             PG8_LDA(At, 1, 1); PG8_STAGE(PG8_SB(1, 0), b3, voffB); PG8_STAGE(PG8_SB(1, 1), b3 + hstep, voffB); PG8_STAGE(PG8_SA(1, 0), a3, voffA);
;             PG8_WAIT_V(8); PG8_WAIT_L(0); PG8_BAR; PG8_MMA(1, 0, At, B0); PG8_MMA(1, 1, At, B1); PG8_BAR; PG8_SCHED;
;         }
;         if (wr == 0) PG8_BAR;
	s_add_i32 s12, s43, s25
	v_lshl_add_u64 v[208:209], v[208:209], 0, s[46:47]
	s_mov_b32 m0, s12
	ds_read_b128 v[176:179], v146 offset:49152
	ds_read_b128 v[180:183], v146 offset:50176
	ds_read_b128 v[184:187], v146 offset:51200
	ds_read_b128 v[188:191], v146 offset:52224
	ds_read_b128 v[192:195], v146 offset:53248
	ds_read_b128 v[196:199], v146 offset:54272
	ds_read_b128 v[200:203], v146 offset:55296
	ds_read_b128 v[204:207], v146 offset:56320
	global_load_lds_dwordx4 v[208:209], off
	s_add_i32 m0, s12, 0x2000
	s_add_u32 s10, s10, 0x80080
	v_lshl_add_u64 v[208:209], v[212:213], 0, s[46:47]
	s_addc_u32 s11, s11, 0
	s_add_i32 s12, s44, s25
	global_load_lds_dwordx4 v[208:209], off
	v_lshl_add_u64 v[208:209], s[10:11], 0, v[210:211]
	s_mov_b32 m0, s12
	s_nop 0
	global_load_lds_dwordx4 v[208:209], off
	v_lshl_add_u64 v[208:209], s[10:11], 0, v[128:129]
	s_add_i32 m0, s12, 0x2000
	s_nop 0
	global_load_lds_dwordx4 v[208:209], off
	v_lshl_add_u64 v[208:209], v[214:215], 0, s[46:47]
	s_mov_b32 m0, s30
	s_nop 0
	global_load_lds_dwordx4 v[208:209], off
	v_lshl_add_u64 v[208:209], v[216:217], 0, s[46:47]
	s_mov_b32 m0, s31
	s_nop 0
	global_load_lds_dwordx4 v[208:209], off
	s_waitcnt vmcnt(8)
	s_waitcnt lgkmcnt(0)
	s_barrier
	s_waitcnt lgkmcnt(0)
	v_mfma_f32_16x16x32_bf16 v[60:63], v[140:143], v[176:179], v[60:63]
	v_mfma_f32_16x16x32_bf16 v[56:59], v[152:155], v[176:179], v[56:59]
	v_mfma_f32_16x16x32_bf16 v[48:51], v[140:143], v[184:187], v[48:51]
	v_mfma_f32_16x16x32_bf16 v[40:43], v[152:155], v[184:187], v[40:43]
	v_mfma_f32_16x16x32_bf16 v[32:35], v[140:143], v[192:195], v[32:35]
	v_mfma_f32_16x16x32_bf16 v[24:27], v[152:155], v[192:195], v[24:27]
	v_mfma_f32_16x16x32_bf16 v[16:19], v[140:143], v[200:203], v[16:19]
	v_mfma_f32_16x16x32_bf16 v[8:11], v[152:155], v[200:203], v[8:11]
	v_mfma_f32_16x16x32_bf16 v[60:63], v[148:151], v[180:183], v[60:63]
	v_mfma_f32_16x16x32_bf16 v[56:59], v[156:159], v[180:183], v[56:59]
	v_mfma_f32_16x16x32_bf16 v[48:51], v[148:151], v[188:191], v[48:51]
	v_mfma_f32_16x16x32_bf16 v[40:43], v[156:159], v[188:191], v[40:43]
	v_mfma_f32_16x16x32_bf16 v[32:35], v[148:151], v[196:199], v[32:35]
	v_mfma_f32_16x16x32_bf16 v[24:27], v[156:159], v[196:199], v[24:27]
	v_mfma_f32_16x16x32_bf16 v[16:19], v[148:151], v[204:207], v[16:19]
	v_mfma_f32_16x16x32_bf16 v[8:11], v[156:159], v[204:207], v[8:11]
	v_mfma_f32_16x16x32_bf16 v[52:55], v[160:163], v[176:179], v[52:55]
	v_mfma_f32_16x16x32_bf16 v[44:47], v[168:171], v[176:179], v[44:47]
	v_mfma_f32_16x16x32_bf16 v[36:39], v[160:163], v[184:187], v[36:39]
	v_mfma_f32_16x16x32_bf16 v[28:31], v[168:171], v[184:187], v[28:31]
	v_mfma_f32_16x16x32_bf16 v[20:23], v[160:163], v[192:195], v[20:23]
	v_mfma_f32_16x16x32_bf16 v[12:15], v[168:171], v[192:195], v[12:15]
	v_mfma_f32_16x16x32_bf16 v[4:7], v[160:163], v[200:203], v[4:7]
	v_mfma_f32_16x16x32_bf16 v[0:3], v[168:171], v[200:203], v[0:3]
	v_mfma_f32_16x16x32_bf16 v[52:55], v[164:167], v[180:183], v[52:55]
	v_mfma_f32_16x16x32_bf16 v[44:47], v[172:175], v[180:183], v[44:47]
	v_mfma_f32_16x16x32_bf16 v[36:39], v[164:167], v[188:191], v[36:39]
	v_mfma_f32_16x16x32_bf16 v[28:31], v[172:175], v[188:191], v[28:31]
	v_mfma_f32_16x16x32_bf16 v[20:23], v[164:167], v[196:199], v[20:23]
	v_mfma_f32_16x16x32_bf16 v[12:15], v[172:175], v[196:199], v[12:15]
	v_mfma_f32_16x16x32_bf16 v[4:7], v[164:167], v[204:207], v[4:7]
	v_mfma_f32_16x16x32_bf16 v[0:3], v[172:175], v[204:207], v[0:3]
	s_barrier
	s_add_i32 s42, s42, 2
	s_add_u32 s22, s22, 0x100
	s_addc_u32 s23, s23, 0
	s_add_u32 s40, s40, 0x100
	s_addc_u32 s41, s41, 0
	s_cmp_gt_u32 s42, 29
	s_cbranch_scc0 .LBB0_324
	s_and_b64 vcc, exec, s[8:9]
	s_cbranch_vccz .LBB0_327
	s_barrier

; #define PG8_STAGE(bufoff, gbase, voff) do { _Pragma("unroll") for (int _i = 0; _i < 2; ++_i) \
;         __builtin_amdgcn_global_load_lds((const unsigned*)((const char*)(gbase) + (voff)[_i]), (LAS unsigned*)(lds + (bufoff) + ldsw + _i * 8192), 16, 0, 0); } while (0)
; #define PG8_LDA(dst, b, h) do { _Pragma("unroll") for (int m = 0; m < 4; ++m) _Pragma("unroll") for (int k = 0; k < 2; ++k) dst[m][k] = *(const LAS bf16x8*)(lds + PG8_SA(b, h) + aoff + m * 2048 + k * 1024); } while (0)
; #define PG8_LDB(dst, b, h) do { _Pragma("unroll") for (int n = 0; n < 2; ++n) _Pragma("unroll") for (int k = 0; k < 2; ++k) dst[n][k] = *(const LAS bf16x8*)(lds + PG8_SB(b, h) + boff + n * 2048 + k * 1024); } while (0)
; #define PG8_MMA(ai, bj, At, Bt) do { __builtin_amdgcn_s_setprio(1); _Pragma("unroll") for (int m = 0; m < 4; ++m) _Pragma("unroll") for (int n = 0; n < 2; ++n) _Pragma("unroll") for (int k = 0; k < 2; ++k) \
;         acc[ai][bj][m][n] = __builtin_amdgcn_mfma_f32_16x16x32_bf16(Bt[n][k], At[m][k], acc[ai][bj][m][n], 0, 0, 0); __builtin_amdgcn_s_setprio(0); } while (0)
; #define PG8_WAIT_V(n) asm volatile("s_waitcnt vmcnt(" #n ")" ::: "memory")
; #define PG8_WAIT_L(n) asm volatile("s_waitcnt lgkmcnt(" #n ")" ::: "memory")
; #define PG8_BAR __builtin_amdgcn_s_barrier()
; template <class Epi, class Sched>
; __device__ __forceinline__ void gemm_phase(LAS unsigned char* lds, const Gemm g, const Sched& S, const Epi& E, const int wv) {
;     ...
;         for (int t = 0; t < nt; t += 2) {
;             const bool last = (t == nt - 2);
;             const char* a1 = cA + (size_t)(t + 1) * kstep;
;             const char* a2 = last ? nA : cA + (size_t)(t + 2) * kstep; const char* b2 = last ? nB : cB + (size_t)(t + 2) * kstep;
;             const char* a3 = a2 + kstep; const char* b3 = b2 + kstep;
;             if (last && has_next) S.a_ready(nxt);
;             PG8_LDB(B0, 0, 0); PG8_LDB(B1, 0, 1); PG8_SCHED; PG8_LDA(At, 0, 0); PG8_STAGE(PG8_SA(1, 1), a1 + hstep, voffA);
;             PG8_WAIT_V(8); PG8_WAIT_L(0); PG8_BAR; PG8_MMA(0, 0, At, B0); PG8_MMA(0, 1, At, B1); PG8_BAR; PG8_SCHED;
;             PG8_LDA(At, 0, 1); PG8_STAGE(PG8_SB(0, 0), b2, voffB); PG8_STAGE(PG8_SB(0, 1), b2 + hstep, voffB); PG8_STAGE(PG8_SA(0, 0), a2, voffA);
;             PG8_WAIT_V(8); PG8_WAIT_L(0); PG8_BAR; PG8_MMA(1, 0, At, B0); PG8_MMA(1, 1, At, B1); PG8_BAR; PG8_SCHED;
.LBB0_346:
	s_add_u32 s10, s16, 0xfff80080
	s_addc_u32 s11, s17, -1
	s_add_i32 s43, 0, 0x10000
	s_cmp_eq_u32 s42, 28
	s_cselect_b32 s13, s19, s11
	s_cselect_b32 s12, s37, s10
	v_add_u32_e32 v152, s43, v155
	s_cselect_b32 s11, s15, s41
	s_cselect_b32 s10, s38, s40
	s_add_i32 s52, 0, 0x14000
	ds_read_b128 v[140:143], v152
	ds_read_b128 v[144:147], v152 offset:1024
	ds_read_b128 v[148:151], v152 offset:2048
	ds_read_b128 v[158:161], v152 offset:3072
	v_add_u32_e32 v152, s52, v155
	ds_read_b128 v[162:165], v152
	ds_read_b128 v[166:169], v152 offset:1024
	ds_read_b128 v[170:173], v152 offset:2048
	ds_read_b128 v[174:177], v152 offset:3072
	v_lshl_add_u64 v[152:153], s[16:17], 0, v[136:137]
	s_add_i32 m0, s26, 0xc000
	ds_read_b128 v[178:181], v157
	ds_read_b128 v[182:185], v157 offset:1024
	ds_read_b128 v[186:189], v157 offset:2048
	ds_read_b128 v[190:193], v157 offset:3072
	ds_read_b128 v[194:197], v157 offset:4096
	ds_read_b128 v[198:201], v157 offset:5120
	ds_read_b128 v[202:205], v157 offset:6144
	ds_read_b128 v[206:209], v157 offset:7168
	global_load_lds_dwordx4 v[152:153], off
	v_lshl_add_u64 v[152:153], s[16:17], 0, v[138:139]
	s_add_i32 m0, s26, 0xe000
	s_nop 0
	global_load_lds_dwordx4 v[152:153], off
	s_waitcnt vmcnt(8)
	s_waitcnt lgkmcnt(0)
	s_barrier
	s_waitcnt lgkmcnt(0)
	v_mfma_f32_16x16x32_bf16 v[124:127], v[140:143], v[178:181], v[124:127]
	v_mfma_f32_16x16x32_bf16 v[116:119], v[148:151], v[178:181], v[116:119]
	v_mfma_f32_16x16x32_bf16 v[108:111], v[140:143], v[186:189], v[108:111]
	v_mfma_f32_16x16x32_bf16 v[100:103], v[148:151], v[186:189], v[100:103]
	v_mfma_f32_16x16x32_bf16 v[92:95], v[140:143], v[194:197], v[92:95]
	v_mfma_f32_16x16x32_bf16 v[84:87], v[148:151], v[194:197], v[84:87]
	v_mfma_f32_16x16x32_bf16 v[76:79], v[140:143], v[202:205], v[76:79]
	v_mfma_f32_16x16x32_bf16 v[68:71], v[148:151], v[202:205], v[68:71]
	v_mfma_f32_16x16x32_bf16 v[124:127], v[144:147], v[182:185], v[124:127]
	v_mfma_f32_16x16x32_bf16 v[116:119], v[158:161], v[182:185], v[116:119]
	v_mfma_f32_16x16x32_bf16 v[108:111], v[144:147], v[190:193], v[108:111]
	v_mfma_f32_16x16x32_bf16 v[100:103], v[158:161], v[190:193], v[100:103]
	v_mfma_f32_16x16x32_bf16 v[92:95], v[144:147], v[198:201], v[92:95]
	v_mfma_f32_16x16x32_bf16 v[84:87], v[158:161], v[198:201], v[84:87]
	v_mfma_f32_16x16x32_bf16 v[76:79], v[144:147], v[206:209], v[76:79]
	v_mfma_f32_16x16x32_bf16 v[68:71], v[158:161], v[206:209], v[68:71]
	v_mfma_f32_16x16x32_bf16 v[120:123], v[162:165], v[178:181], v[120:123]
	v_mfma_f32_16x16x32_bf16 v[112:115], v[170:173], v[178:181], v[112:115]
	v_mfma_f32_16x16x32_bf16 v[104:107], v[162:165], v[186:189], v[104:107]
	v_mfma_f32_16x16x32_bf16 v[96:99], v[170:173], v[186:189], v[96:99]
	v_mfma_f32_16x16x32_bf16 v[88:91], v[162:165], v[194:197], v[88:91]
	v_mfma_f32_16x16x32_bf16 v[80:83], v[170:173], v[194:197], v[80:83]
	v_mfma_f32_16x16x32_bf16 v[72:75], v[162:165], v[202:205], v[72:75]
	v_mfma_f32_16x16x32_bf16 v[64:67], v[170:173], v[202:205], v[64:67]
	v_mfma_f32_16x16x32_bf16 v[120:123], v[166:169], v[182:185], v[120:123]
	v_mfma_f32_16x16x32_bf16 v[112:115], v[174:177], v[182:185], v[112:115]
	v_mfma_f32_16x16x32_bf16 v[104:107], v[166:169], v[190:193], v[104:107]
	v_mfma_f32_16x16x32_bf16 v[96:99], v[174:177], v[190:193], v[96:99]
	v_mfma_f32_16x16x32_bf16 v[88:91], v[166:169], v[198:201], v[88:91]
	v_mfma_f32_16x16x32_bf16 v[80:83], v[174:177], v[198:201], v[80:83]
	v_mfma_f32_16x16x32_bf16 v[72:75], v[166:169], v[206:209], v[72:75]
	v_mfma_f32_16x16x32_bf16 v[64:67], v[174:177], v[206:209], v[64:67]
	s_barrier
	s_add_i32 s43, s43, s25
	v_lshl_add_u64 v[152:153], s[10:11], 0, v[132:133]
	s_mov_b32 m0, s43
	ds_read_b128 v[178:181], v157 offset:16384
	ds_read_b128 v[182:185], v157 offset:17408
	ds_read_b128 v[186:189], v157 offset:18432
	ds_read_b128 v[190:193], v157 offset:19456
	ds_read_b128 v[194:197], v157 offset:20480
	ds_read_b128 v[198:201], v157 offset:21504
	ds_read_b128 v[202:205], v157 offset:22528
	ds_read_b128 v[206:209], v157 offset:23552
	global_load_lds_dwordx4 v[152:153], off
	s_add_i32 m0, s43, 0x2000
	s_add_u32 s44, s10, 0x80000
	v_lshl_add_u64 v[212:213], s[10:11], 0, v[128:129]
	s_addc_u32 s45, s11, 0
	s_add_i32 s43, s52, s25
	global_load_lds_dwordx4 v[212:213], off
	v_lshl_add_u64 v[214:215], s[44:45], 0, v[132:133]
	s_mov_b32 m0, s43
	v_lshl_add_u64 v[216:217], s[12:13], 0, v[130:131]
	global_load_lds_dwordx4 v[214:215], off
	v_lshl_add_u64 v[214:215], s[44:45], 0, v[128:129]
	s_add_i32 m0, s43, 0x2000
	s_nop 0
	global_load_lds_dwordx4 v[214:215], off
	v_lshl_add_u64 v[214:215], s[12:13], 0, v[134:135]
	s_mov_b32 m0, s26
	s_nop 0
	global_load_lds_dwordx4 v[214:215], off
	s_mov_b32 m0, s27
	s_nop 0
	global_load_lds_dwordx4 v[216:217], off
	s_waitcnt vmcnt(8)
	s_waitcnt lgkmcnt(0)
	s_barrier
; #define PG8_STAGE(bufoff, gbase, voff) do { _Pragma("unroll") for (int _i = 0; _i < 2; ++_i) \
;         __builtin_amdgcn_global_load_lds((const unsigned*)((const char*)(gbase) + (voff)[_i]), (LAS unsigned*)(lds + (bufoff) + ldsw + _i * 8192), 16, 0, 0); } while (0)
; #define PG8_LDA(dst, b, h) do { _Pragma("unroll") for (int m = 0; m < 4; ++m) _Pragma("unroll") for (int k = 0; k < 2; ++k) dst[m][k] = *(const LAS bf16x8*)(lds + PG8_SA(b, h) + aoff + m * 2048 + k * 1024); } while (0)
; #define PG8_LDB(dst, b, h) do { _Pragma("unroll") for (int n = 0; n < 2; ++n) _Pragma("unroll") for (int k = 0; k < 2; ++k) dst[n][k] = *(const LAS bf16x8*)(lds + PG8_SB(b, h) + boff + n * 2048 + k * 1024); } while (0)
; #define PG8_MMA(ai, bj, At, Bt) do { __builtin_amdgcn_s_setprio(1); _Pragma("unroll") for (int m = 0; m < 4; ++m) _Pragma("unroll") for (int n = 0; n < 2; ++n) _Pragma("unroll") for (int k = 0; k < 2; ++k) \
;         acc[ai][bj][m][n] = __builtin_amdgcn_mfma_f32_16x16x32_bf16(Bt[n][k], At[m][k], acc[ai][bj][m][n], 0, 0, 0); __builtin_amdgcn_s_setprio(0); } while (0)
; #define PG8_WAIT_V(n) asm volatile("s_waitcnt vmcnt(" #n ")" ::: "memory")
; #define PG8_WAIT_L(n) asm volatile("s_waitcnt lgkmcnt(" #n ")" ::: "memory")
; #define PG8_BAR __builtin_amdgcn_s_barrier()
; #define PG8_SCHED __builtin_amdgcn_sched_barrier(0)
; template <class Epi, class Sched>
; __device__ __forceinline__ void gemm_phase(LAS unsigned char* lds, const Gemm g, const Sched& S, const Epi& E, const int wv) {
;     ...
;             PG8_WAIT_V(8); PG8_WAIT_L(0); PG8_BAR; PG8_MMA(1, 0, At, B0); PG8_MMA(1, 1, At, B1); PG8_BAR; PG8_SCHED;
;             PG8_LDB(B0, 1, 0); PG8_LDB(B1, 1, 1); PG8_SCHED; PG8_LDA(At, 1, 0); PG8_STAGE(PG8_SA(0, 1), a2 + hstep, voffA);
;             PG8_WAIT_V(8); PG8_WAIT_L(0); PG8_BAR; PG8_MMA(0, 0, At, B0); PG8_MMA(0, 1, At, B1); PG8_BAR; PG8_SCHED;
	s_waitcnt lgkmcnt(0)
	v_mfma_f32_16x16x32_bf16 v[60:63], v[140:143], v[178:181], v[60:63]
	v_mfma_f32_16x16x32_bf16 v[52:55], v[148:151], v[178:181], v[52:55]
	v_mfma_f32_16x16x32_bf16 v[44:47], v[140:143], v[186:189], v[44:47]
	v_mfma_f32_16x16x32_bf16 v[36:39], v[148:151], v[186:189], v[36:39]
	v_mfma_f32_16x16x32_bf16 v[28:31], v[140:143], v[194:197], v[28:31]
	v_mfma_f32_16x16x32_bf16 v[20:23], v[148:151], v[194:197], v[20:23]
	v_mfma_f32_16x16x32_bf16 v[12:15], v[140:143], v[202:205], v[12:15]
	v_mfma_f32_16x16x32_bf16 v[4:7], v[148:151], v[202:205], v[4:7]
	v_mfma_f32_16x16x32_bf16 v[60:63], v[144:147], v[182:185], v[60:63]
	v_mfma_f32_16x16x32_bf16 v[52:55], v[158:161], v[182:185], v[52:55]
	v_mfma_f32_16x16x32_bf16 v[44:47], v[144:147], v[190:193], v[44:47]
	v_mfma_f32_16x16x32_bf16 v[36:39], v[158:161], v[190:193], v[36:39]
	v_mfma_f32_16x16x32_bf16 v[28:31], v[144:147], v[198:201], v[28:31]
	v_mfma_f32_16x16x32_bf16 v[20:23], v[158:161], v[198:201], v[20:23]
	v_mfma_f32_16x16x32_bf16 v[12:15], v[144:147], v[206:209], v[12:15]
	v_mfma_f32_16x16x32_bf16 v[4:7], v[158:161], v[206:209], v[4:7]
	v_mfma_f32_16x16x32_bf16 v[56:59], v[162:165], v[178:181], v[56:59]
	v_mfma_f32_16x16x32_bf16 v[48:51], v[170:173], v[178:181], v[48:51]
	v_mfma_f32_16x16x32_bf16 v[40:43], v[162:165], v[186:189], v[40:43]
	v_mfma_f32_16x16x32_bf16 v[32:35], v[170:173], v[186:189], v[32:35]
	v_mfma_f32_16x16x32_bf16 v[24:27], v[162:165], v[194:197], v[24:27]
	v_mfma_f32_16x16x32_bf16 v[16:19], v[170:173], v[194:197], v[16:19]
	v_mfma_f32_16x16x32_bf16 v[8:11], v[162:165], v[202:205], v[8:11]
	v_mfma_f32_16x16x32_bf16 v[0:3], v[170:173], v[202:205], v[0:3]
	v_mfma_f32_16x16x32_bf16 v[56:59], v[166:169], v[182:185], v[56:59]
	v_mfma_f32_16x16x32_bf16 v[48:51], v[174:177], v[182:185], v[48:51]
	v_mfma_f32_16x16x32_bf16 v[40:43], v[166:169], v[190:193], v[40:43]
	v_mfma_f32_16x16x32_bf16 v[32:35], v[174:177], v[190:193], v[32:35]
	v_mfma_f32_16x16x32_bf16 v[24:27], v[166:169], v[198:201], v[24:27]
	v_mfma_f32_16x16x32_bf16 v[16:19], v[174:177], v[198:201], v[16:19]
	v_mfma_f32_16x16x32_bf16 v[8:11], v[166:169], v[206:209], v[8:11]
	v_mfma_f32_16x16x32_bf16 v[0:3], v[174:177], v[206:209], v[0:3]
	s_barrier
	s_add_i32 s43, 0, 0x18000
	s_add_i32 s44, 0, 0x1c000
	v_add_u32_e32 v158, s43, v155
	v_add_u32_e32 v174, s44, v155
	ds_read_b128 v[140:143], v158
	ds_read_b128 v[144:147], v158 offset:1024
	ds_read_b128 v[148:151], v158 offset:2048
	ds_read_b128 v[158:161], v158 offset:3072
	ds_read_b128 v[162:165], v174
	ds_read_b128 v[166:169], v174 offset:1024
	ds_read_b128 v[170:173], v174 offset:2048
	ds_read_b128 v[174:177], v174 offset:3072
	s_add_u32 s12, s12, 0x80000
	s_addc_u32 s13, s13, 0
	s_mov_b32 m0, s28
	v_lshl_add_u64 v[218:219], s[12:13], 0, v[134:135]
	ds_read_b128 v[178:181], v157 offset:32768
	ds_read_b128 v[182:185], v157 offset:33792
	ds_read_b128 v[186:189], v157 offset:34816
	ds_read_b128 v[190:193], v157 offset:35840
	ds_read_b128 v[194:197], v157 offset:36864
	ds_read_b128 v[198:201], v157 offset:37888
	ds_read_b128 v[202:205], v157 offset:38912
	ds_read_b128 v[206:209], v157 offset:39936
	global_load_lds_dwordx4 v[218:219], off
	v_lshl_add_u64 v[218:219], s[12:13], 0, v[130:131]
	s_mov_b32 m0, s29
	s_nop 0
	global_load_lds_dwordx4 v[218:219], off
	s_waitcnt vmcnt(8)
	s_waitcnt lgkmcnt(0)
	s_barrier
	s_waitcnt lgkmcnt(0)
	v_mfma_f32_16x16x32_bf16 v[124:127], v[140:143], v[178:181], v[124:127]
	v_mfma_f32_16x16x32_bf16 v[116:119], v[148:151], v[178:181], v[116:119]
	v_mfma_f32_16x16x32_bf16 v[108:111], v[140:143], v[186:189], v[108:111]
	v_mfma_f32_16x16x32_bf16 v[100:103], v[148:151], v[186:189], v[100:103]
	v_mfma_f32_16x16x32_bf16 v[92:95], v[140:143], v[194:197], v[92:95]
	v_mfma_f32_16x16x32_bf16 v[84:87], v[148:151], v[194:197], v[84:87]
	v_mfma_f32_16x16x32_bf16 v[76:79], v[140:143], v[202:205], v[76:79]
	v_mfma_f32_16x16x32_bf16 v[68:71], v[148:151], v[202:205], v[68:71]
	v_mfma_f32_16x16x32_bf16 v[124:127], v[144:147], v[182:185], v[124:127]
	v_mfma_f32_16x16x32_bf16 v[116:119], v[158:161], v[182:185], v[116:119]
	v_mfma_f32_16x16x32_bf16 v[108:111], v[144:147], v[190:193], v[108:111]
	v_mfma_f32_16x16x32_bf16 v[100:103], v[158:161], v[190:193], v[100:103]
	v_mfma_f32_16x16x32_bf16 v[92:95], v[144:147], v[198:201], v[92:95]
	v_mfma_f32_16x16x32_bf16 v[84:87], v[158:161], v[198:201], v[84:87]
	v_mfma_f32_16x16x32_bf16 v[76:79], v[144:147], v[206:209], v[76:79]
	v_mfma_f32_16x16x32_bf16 v[68:71], v[158:161], v[206:209], v[68:71]
	v_mfma_f32_16x16x32_bf16 v[120:123], v[162:165], v[178:181], v[120:123]
	v_mfma_f32_16x16x32_bf16 v[112:115], v[170:173], v[178:181], v[112:115]
	v_mfma_f32_16x16x32_bf16 v[104:107], v[162:165], v[186:189], v[104:107]
	v_mfma_f32_16x16x32_bf16 v[96:99], v[170:173], v[186:189], v[96:99]
	v_mfma_f32_16x16x32_bf16 v[88:91], v[162:165], v[194:197], v[88:91]
	v_mfma_f32_16x16x32_bf16 v[80:83], v[170:173], v[194:197], v[80:83]
	v_mfma_f32_16x16x32_bf16 v[72:75], v[162:165], v[202:205], v[72:75]
	v_mfma_f32_16x16x32_bf16 v[64:67], v[170:173], v[202:205], v[64:67]
	v_mfma_f32_16x16x32_bf16 v[120:123], v[166:169], v[182:185], v[120:123]
	v_mfma_f32_16x16x32_bf16 v[112:115], v[174:177], v[182:185], v[112:115]
	v_mfma_f32_16x16x32_bf16 v[104:107], v[166:169], v[190:193], v[104:107]
	v_mfma_f32_16x16x32_bf16 v[96:99], v[174:177], v[190:193], v[96:99]
	v_mfma_f32_16x16x32_bf16 v[88:91], v[166:169], v[198:201], v[88:91]
	v_mfma_f32_16x16x32_bf16 v[80:83], v[174:177], v[198:201], v[80:83]
	v_mfma_f32_16x16x32_bf16 v[72:75], v[166:169], v[206:209], v[72:75]
	v_mfma_f32_16x16x32_bf16 v[64:67], v[174:177], v[206:209], v[64:67]
	s_barrier
; #define PG8_STAGE(bufoff, gbase, voff) do { _Pragma("unroll") for (int _i = 0; _i < 2; ++_i) \
;         __builtin_amdgcn_global_load_lds((const unsigned*)((const char*)(gbase) + (voff)[_i]), (LAS unsigned*)(lds + (bufoff) + ldsw + _i * 8192), 16, 0, 0); } while (0)
; #define PG8_LDA(dst, b, h) do { _Pragma("unroll") for (int m = 0; m < 4; ++m) _Pragma("unroll") for (int k = 0; k < 2; ++k) dst[m][k] = *(const LAS bf16x8*)(lds + PG8_SA(b, h) + aoff + m * 2048 + k * 1024); } while (0)
; #define PG8_MMA(ai, bj, At, Bt) do { __builtin_amdgcn_s_setprio(1); _Pragma("unroll") for (int m = 0; m < 4; ++m) _Pragma("unroll") for (int n = 0; n < 2; ++n) _Pragma("unroll") for (int k = 0; k < 2; ++k) \
;         acc[ai][bj][m][n] = __builtin_amdgcn_mfma_f32_16x16x32_bf16(Bt[n][k], At[m][k], acc[ai][bj][m][n], 0, 0, 0); __builtin_amdgcn_s_setprio(0); } while (0)
; #define PG8_WAIT_V(n) asm volatile("s_waitcnt vmcnt(" #n ")" ::: "memory")
; #define PG8_WAIT_L(n) asm volatile("s_waitcnt lgkmcnt(" #n ")" ::: "memory")
; #define PG8_BAR __builtin_amdgcn_s_barrier()
; #define PG8_SCHED __builtin_amdgcn_sched_barrier(0)
; template <class Epi, class Sched>
; __device__ __forceinline__ void gemm_phase(LAS unsigned char* lds, const Gemm g, const Sched& S, const Epi& E, const int wv) {
;     ...
;             PG8_LDA(At, 1, 1); PG8_STAGE(PG8_SB(1, 0), b3, voffB); PG8_STAGE(PG8_SB(1, 1), b3 + hstep, voffB); PG8_STAGE(PG8_SA(1, 0), a3, voffA);
;             PG8_WAIT_V(8); PG8_WAIT_L(0); PG8_BAR; PG8_MMA(1, 0, At, B0); PG8_MMA(1, 1, At, B1); PG8_BAR; PG8_SCHED;
;         }
;         if (wr == 0) PG8_BAR;
	s_add_i32 s12, s43, s25
	v_lshl_add_u64 v[152:153], v[152:153], 0, s[46:47]
	s_mov_b32 m0, s12
	ds_read_b128 v[178:181], v157 offset:49152
	ds_read_b128 v[182:185], v157 offset:50176
	ds_read_b128 v[186:189], v157 offset:51200
	ds_read_b128 v[190:193], v157 offset:52224
	ds_read_b128 v[194:197], v157 offset:53248
	ds_read_b128 v[198:201], v157 offset:54272
	ds_read_b128 v[202:205], v157 offset:55296
	ds_read_b128 v[206:209], v157 offset:56320
	global_load_lds_dwordx4 v[152:153], off
	s_add_i32 m0, s12, 0x2000
	s_add_u32 s10, s10, 0x80080
	v_lshl_add_u64 v[152:153], v[212:213], 0, s[46:47]
	s_addc_u32 s11, s11, 0
	s_add_i32 s12, s44, s25
	global_load_lds_dwordx4 v[152:153], off
	v_lshl_add_u64 v[152:153], s[10:11], 0, v[132:133]
	s_mov_b32 m0, s12
	s_nop 0
	global_load_lds_dwordx4 v[152:153], off
	v_lshl_add_u64 v[152:153], s[10:11], 0, v[128:129]
	s_add_i32 m0, s12, 0x2000
	s_nop 0
	global_load_lds_dwordx4 v[152:153], off
	v_lshl_add_u64 v[152:153], v[214:215], 0, s[46:47]
	s_mov_b32 m0, s30
	s_nop 0
	global_load_lds_dwordx4 v[152:153], off
	v_lshl_add_u64 v[152:153], v[216:217], 0, s[46:47]
	s_mov_b32 m0, s31
	s_nop 0
	global_load_lds_dwordx4 v[152:153], off
	s_waitcnt vmcnt(8)
	s_waitcnt lgkmcnt(0)
	s_barrier
	s_waitcnt lgkmcnt(0)
	v_mfma_f32_16x16x32_bf16 v[60:63], v[140:143], v[178:181], v[60:63]
	v_mfma_f32_16x16x32_bf16 v[52:55], v[148:151], v[178:181], v[52:55]
	v_mfma_f32_16x16x32_bf16 v[44:47], v[140:143], v[186:189], v[44:47]
	v_mfma_f32_16x16x32_bf16 v[36:39], v[148:151], v[186:189], v[36:39]
	v_mfma_f32_16x16x32_bf16 v[28:31], v[140:143], v[194:197], v[28:31]
	v_mfma_f32_16x16x32_bf16 v[20:23], v[148:151], v[194:197], v[20:23]
	v_mfma_f32_16x16x32_bf16 v[12:15], v[140:143], v[202:205], v[12:15]
	v_mfma_f32_16x16x32_bf16 v[4:7], v[148:151], v[202:205], v[4:7]
	v_mfma_f32_16x16x32_bf16 v[60:63], v[144:147], v[182:185], v[60:63]
	v_mfma_f32_16x16x32_bf16 v[52:55], v[158:161], v[182:185], v[52:55]
	v_mfma_f32_16x16x32_bf16 v[44:47], v[144:147], v[190:193], v[44:47]
	v_mfma_f32_16x16x32_bf16 v[36:39], v[158:161], v[190:193], v[36:39]
	v_mfma_f32_16x16x32_bf16 v[28:31], v[144:147], v[198:201], v[28:31]
	v_mfma_f32_16x16x32_bf16 v[20:23], v[158:161], v[198:201], v[20:23]
	v_mfma_f32_16x16x32_bf16 v[12:15], v[144:147], v[206:209], v[12:15]
	v_mfma_f32_16x16x32_bf16 v[4:7], v[158:161], v[206:209], v[4:7]
	v_mfma_f32_16x16x32_bf16 v[56:59], v[162:165], v[178:181], v[56:59]
	v_mfma_f32_16x16x32_bf16 v[48:51], v[170:173], v[178:181], v[48:51]
	v_mfma_f32_16x16x32_bf16 v[40:43], v[162:165], v[186:189], v[40:43]
	v_mfma_f32_16x16x32_bf16 v[32:35], v[170:173], v[186:189], v[32:35]
	v_mfma_f32_16x16x32_bf16 v[24:27], v[162:165], v[194:197], v[24:27]
	v_mfma_f32_16x16x32_bf16 v[16:19], v[170:173], v[194:197], v[16:19]
	v_mfma_f32_16x16x32_bf16 v[8:11], v[162:165], v[202:205], v[8:11]
	v_mfma_f32_16x16x32_bf16 v[0:3], v[170:173], v[202:205], v[0:3]
	v_mfma_f32_16x16x32_bf16 v[56:59], v[166:169], v[182:185], v[56:59]
	v_mfma_f32_16x16x32_bf16 v[48:51], v[174:177], v[182:185], v[48:51]
	v_mfma_f32_16x16x32_bf16 v[40:43], v[166:169], v[190:193], v[40:43]
	v_mfma_f32_16x16x32_bf16 v[32:35], v[174:177], v[190:193], v[32:35]
	v_mfma_f32_16x16x32_bf16 v[24:27], v[166:169], v[198:201], v[24:27]
	v_mfma_f32_16x16x32_bf16 v[16:19], v[174:177], v[198:201], v[16:19]
	v_mfma_f32_16x16x32_bf16 v[8:11], v[166:169], v[206:209], v[8:11]
	v_mfma_f32_16x16x32_bf16 v[0:3], v[174:177], v[206:209], v[0:3]
	s_barrier
	s_add_i32 s42, s42, 2
	s_add_u32 s16, s16, 0x100
	s_addc_u32 s17, s17, 0
	s_add_u32 s40, s40, 0x100
	s_addc_u32 s41, s41, 0
	s_cmp_gt_u32 s42, 29
	s_cbranch_scc0 .LBB0_346
	s_and_b64 vcc, exec, s[8:9]
	s_cbranch_vccz .LBB0_349
	s_barrier
